# baseline (speedup 1.0000x reference)
.Lbk64_350:
	s_waitcnt vmcnt(0)
	s_barrier
	ds_read_b128 v[192:195], v227
	ds_read_b128 v[196:199], v228
	ds_read_b128 v[200:203], v227 offset:2048
	ds_read_b128 v[204:207], v228 offset:2048
	ds_read_b128 v[208:211], v227 offset:4096
	ds_read_b128 v[212:215], v228 offset:4096
	ds_read_b128 v[216:219], v227 offset:6144
	ds_read_b128 v[220:223], v228 offset:6144
	s_add_u32 s18, s18, 0x80
	s_addc_u32 s19, s19, 0
	s_add_u32 s16, s16, 0x80
	s_addc_u32 s17, s17, 0
	s_waitcnt lgkmcnt(0)
	ds_read_b128 v[154:157], v229 offset:0
	ds_read_b128 v[158:161], v230 offset:0
	ds_read_b128 v[162:165], v229 offset:2048
	ds_read_b128 v[166:169], v230 offset:2048
	s_waitcnt lgkmcnt(2)
	v_mfma_f32_16x16x32_bf16 v[126:129], v[192:195], v[154:157], v[126:129]
	v_mfma_f32_16x16x32_bf16 v[114:117], v[200:203], v[154:157], v[114:117]
	v_mfma_f32_16x16x32_bf16 v[86:89], v[208:211], v[154:157], v[86:89]
	v_mfma_f32_16x16x32_bf16 v[54:57], v[216:219], v[154:157], v[54:57]
	v_readfirstlane_b32 s32, v145
	s_lshl_b32 m0, s32, 3
	v_mov_b32_e32 v226, v224
	global_load_lds_dwordx4 v226, s[18:19]
	v_mfma_f32_16x16x32_bf16 v[126:129], v[196:199], v[158:161], v[126:129]
	v_mfma_f32_16x16x32_bf16 v[114:117], v[204:207], v[158:161], v[114:117]
	v_mfma_f32_16x16x32_bf16 v[86:89], v[212:215], v[158:161], v[86:89]
	v_mfma_f32_16x16x32_bf16 v[54:57], v[220:223], v[158:161], v[54:57]
	s_add_u32 m0, m0, 0x400
	v_add_u32_e32 v226, 0xac00, v224
	global_load_lds_dwordx4 v226, s[18:19]
	ds_read_b128 v[154:157], v229 offset:4096
	ds_read_b128 v[158:161], v230 offset:4096
	s_waitcnt lgkmcnt(2)
	v_mfma_f32_16x16x32_bf16 v[122:125], v[192:195], v[162:165], v[122:125]
	v_mfma_f32_16x16x32_bf16 v[102:105], v[200:203], v[162:165], v[102:105]
	v_mfma_f32_16x16x32_bf16 v[70:73], v[208:211], v[162:165], v[70:73]
	v_mfma_f32_16x16x32_bf16 v[38:41], v[216:219], v[162:165], v[38:41]
	s_add_u32 m0, m0, 0x400
	v_add_u32_e32 v226, 0x15800, v224
	global_load_lds_dwordx4 v226, s[18:19]
	v_mfma_f32_16x16x32_bf16 v[122:125], v[196:199], v[166:169], v[122:125]
	v_mfma_f32_16x16x32_bf16 v[102:105], v[204:207], v[166:169], v[102:105]
	v_mfma_f32_16x16x32_bf16 v[70:73], v[212:215], v[166:169], v[70:73]
	v_mfma_f32_16x16x32_bf16 v[38:41], v[220:223], v[166:169], v[38:41]
	s_add_u32 m0, m0, 0x400
	v_add_u32_e32 v226, 0x20400, v224
	global_load_lds_dwordx4 v226, s[18:19]
	ds_read_b128 v[162:165], v229 offset:6144
	ds_read_b128 v[166:169], v230 offset:6144
	s_waitcnt lgkmcnt(2)
	v_mfma_f32_16x16x32_bf16 v[118:121], v[192:195], v[154:157], v[118:121]
	v_mfma_f32_16x16x32_bf16 v[90:93], v[200:203], v[154:157], v[90:93]
	v_mfma_f32_16x16x32_bf16 v[58:61], v[208:211], v[154:157], v[58:61]
	v_mfma_f32_16x16x32_bf16 v[26:29], v[216:219], v[154:157], v[26:29]
	s_add_u32 m0, m0, 0x400
	v_add_u32_e32 v226, 0x2b000, v224
	global_load_lds_dwordx4 v226, s[18:19]
	v_mfma_f32_16x16x32_bf16 v[118:121], v[196:199], v[158:161], v[118:121]
	v_mfma_f32_16x16x32_bf16 v[90:93], v[204:207], v[158:161], v[90:93]
	v_mfma_f32_16x16x32_bf16 v[58:61], v[212:215], v[158:161], v[58:61]
	v_mfma_f32_16x16x32_bf16 v[26:29], v[220:223], v[158:161], v[26:29]
	s_add_u32 m0, m0, 0x400
	v_add_u32_e32 v226, 0x35c00, v224
	global_load_lds_dwordx4 v226, s[18:19]
	ds_read_b128 v[154:157], v229 offset:8192
	ds_read_b128 v[158:161], v230 offset:8192
	s_waitcnt lgkmcnt(2)
	v_mfma_f32_16x16x32_bf16 v[110:113], v[192:195], v[162:165], v[110:113]
	v_mfma_f32_16x16x32_bf16 v[78:81], v[200:203], v[162:165], v[78:81]
	v_mfma_f32_16x16x32_bf16 v[46:49], v[208:211], v[162:165], v[46:49]
	v_mfma_f32_16x16x32_bf16 v[18:21], v[216:219], v[162:165], v[18:21]
	s_add_u32 m0, m0, 0x400
	v_add_u32_e32 v226, 0x40800, v224
	global_load_lds_dwordx4 v226, s[18:19]
	v_mfma_f32_16x16x32_bf16 v[110:113], v[196:199], v[166:169], v[110:113]
	v_mfma_f32_16x16x32_bf16 v[78:81], v[204:207], v[166:169], v[78:81]
	v_mfma_f32_16x16x32_bf16 v[46:49], v[212:215], v[166:169], v[46:49]
	v_mfma_f32_16x16x32_bf16 v[18:21], v[220:223], v[166:169], v[18:21]
	s_add_u32 m0, m0, 0x400
	v_add_u32_e32 v226, 0x4b400, v224
	global_load_lds_dwordx4 v226, s[18:19]
	ds_read_b128 v[162:165], v229 offset:10240
	ds_read_b128 v[166:169], v230 offset:10240
	s_waitcnt lgkmcnt(2)
	v_mfma_f32_16x16x32_bf16 v[106:109], v[192:195], v[154:157], v[106:109]
	v_mfma_f32_16x16x32_bf16 v[74:77], v[200:203], v[154:157], v[74:77]
	v_mfma_f32_16x16x32_bf16 v[42:45], v[208:211], v[154:157], v[42:45]
	v_mfma_f32_16x16x32_bf16 v[14:17], v[216:219], v[154:157], v[14:17]
	s_add_u32 m0, s25, 44
	s_and_b32 m0, m0, 1
	s_lshl_b32 m0, m0, 14
	s_add_u32 m0, m0, 0x8000
	v_readfirstlane_b32 s32, v145
	s_lshl_b32 s32, s32, 2
	s_add_u32 m0, m0, s32
	v_mov_b32_e32 v226, v225
	global_load_lds_dwordx4 v226, s[16:17]
	v_mfma_f32_16x16x32_bf16 v[106:109], v[196:199], v[158:161], v[106:109]
	v_mfma_f32_16x16x32_bf16 v[74:77], v[204:207], v[158:161], v[74:77]
	v_mfma_f32_16x16x32_bf16 v[42:45], v[212:215], v[158:161], v[42:45]
	v_mfma_f32_16x16x32_bf16 v[14:17], v[220:223], v[158:161], v[14:17]
	s_add_u32 m0, m0, 0x400
	v_add_u32_e32 v226, 0xac00, v225
	global_load_lds_dwordx4 v226, s[16:17]
	ds_read_b128 v[154:157], v229 offset:12288
	ds_read_b128 v[158:161], v230 offset:12288
	s_waitcnt lgkmcnt(2)
	v_mfma_f32_16x16x32_bf16 v[98:101], v[192:195], v[162:165], v[98:101]
	v_mfma_f32_16x16x32_bf16 v[66:69], v[200:203], v[162:165], v[66:69]
	v_mfma_f32_16x16x32_bf16 v[34:37], v[208:211], v[162:165], v[34:37]
	v_mfma_f32_16x16x32_bf16 v[10:13], v[216:219], v[162:165], v[10:13]
	s_add_u32 m0, m0, 0x400
	v_add_u32_e32 v226, 0x15800, v225
	global_load_lds_dwordx4 v226, s[16:17]
	v_mfma_f32_16x16x32_bf16 v[98:101], v[196:199], v[166:169], v[98:101]
	v_mfma_f32_16x16x32_bf16 v[66:69], v[204:207], v[166:169], v[66:69]
	v_mfma_f32_16x16x32_bf16 v[34:37], v[212:215], v[166:169], v[34:37]
	v_mfma_f32_16x16x32_bf16 v[10:13], v[220:223], v[166:169], v[10:13]
	s_add_u32 m0, m0, 0x400
	v_add_u32_e32 v226, 0x20400, v225
	global_load_lds_dwordx4 v226, s[16:17]
	ds_read_b128 v[162:165], v229 offset:14336
	ds_read_b128 v[166:169], v230 offset:14336
	s_waitcnt lgkmcnt(2)
	v_mfma_f32_16x16x32_bf16 v[94:97], v[192:195], v[154:157], v[94:97]
	v_mfma_f32_16x16x32_bf16 v[62:65], v[200:203], v[154:157], v[62:65]
	v_mfma_f32_16x16x32_bf16 v[30:33], v[208:211], v[154:157], v[30:33]
	v_mfma_f32_16x16x32_bf16 v[6:9], v[216:219], v[154:157], v[6:9]
	v_mfma_f32_16x16x32_bf16 v[94:97], v[196:199], v[158:161], v[94:97]
	v_mfma_f32_16x16x32_bf16 v[62:65], v[204:207], v[158:161], v[62:65]
	v_mfma_f32_16x16x32_bf16 v[30:33], v[212:215], v[158:161], v[30:33]
	v_mfma_f32_16x16x32_bf16 v[6:9], v[220:223], v[158:161], v[6:9]
	s_waitcnt lgkmcnt(0)
	v_mfma_f32_16x16x32_bf16 v[82:85], v[192:195], v[162:165], v[82:85]
	v_mfma_f32_16x16x32_bf16 v[50:53], v[200:203], v[162:165], v[50:53]
	v_mfma_f32_16x16x32_bf16 v[22:25], v[208:211], v[162:165], v[22:25]
	v_mfma_f32_16x16x32_bf16 v[2:5], v[216:219], v[162:165], v[2:5]
	v_mfma_f32_16x16x32_bf16 v[82:85], v[196:199], v[166:169], v[82:85]
	v_mfma_f32_16x16x32_bf16 v[50:53], v[204:207], v[166:169], v[50:53]
	v_mfma_f32_16x16x32_bf16 v[22:25], v[212:215], v[166:169], v[22:25]
	v_mfma_f32_16x16x32_bf16 v[2:5], v[220:223], v[166:169], v[2:5]
	v_xor_b32_e32 v229, 0x4000, v229
	v_xor_b32_e32 v230, 0x4000, v230
	s_add_i32 s25, s25, 1
	s_cmp_lg_u32 s25, 42
	s_cbranch_scc1 .Lbk64_350
	s_waitcnt vmcnt(0)
	s_barrier
	ds_read_b128 v[192:195], v227
	ds_read_b128 v[196:199], v228
	ds_read_b128 v[200:203], v227 offset:2048
	ds_read_b128 v[204:207], v228 offset:2048
	ds_read_b128 v[208:211], v227 offset:4096
	ds_read_b128 v[212:215], v228 offset:4096
	ds_read_b128 v[216:219], v227 offset:6144
	ds_read_b128 v[220:223], v228 offset:6144
	s_waitcnt lgkmcnt(0)
	ds_read_b128 v[154:157], v229 offset:0
	ds_read_b128 v[158:161], v230 offset:0
	ds_read_b128 v[162:165], v229 offset:2048
	ds_read_b128 v[166:169], v230 offset:2048
	s_waitcnt lgkmcnt(2)
	v_mfma_f32_16x16x32_bf16 v[126:129], v[192:195], v[154:157], v[126:129]
	v_mfma_f32_16x16x32_bf16 v[114:117], v[200:203], v[154:157], v[114:117]
	v_mfma_f32_16x16x32_bf16 v[86:89], v[208:211], v[154:157], v[86:89]
	v_mfma_f32_16x16x32_bf16 v[54:57], v[216:219], v[154:157], v[54:57]
	v_mfma_f32_16x16x32_bf16 v[126:129], v[196:199], v[158:161], v[126:129]
	v_mfma_f32_16x16x32_bf16 v[114:117], v[204:207], v[158:161], v[114:117]
	v_mfma_f32_16x16x32_bf16 v[86:89], v[212:215], v[158:161], v[86:89]
	v_mfma_f32_16x16x32_bf16 v[54:57], v[220:223], v[158:161], v[54:57]
	ds_read_b128 v[154:157], v229 offset:4096
	ds_read_b128 v[158:161], v230 offset:4096
	s_waitcnt lgkmcnt(2)
	v_mfma_f32_16x16x32_bf16 v[122:125], v[192:195], v[162:165], v[122:125]
	v_mfma_f32_16x16x32_bf16 v[102:105], v[200:203], v[162:165], v[102:105]
	v_mfma_f32_16x16x32_bf16 v[70:73], v[208:211], v[162:165], v[70:73]
	v_mfma_f32_16x16x32_bf16 v[38:41], v[216:219], v[162:165], v[38:41]
	v_mfma_f32_16x16x32_bf16 v[122:125], v[196:199], v[166:169], v[122:125]
	v_mfma_f32_16x16x32_bf16 v[102:105], v[204:207], v[166:169], v[102:105]
	v_mfma_f32_16x16x32_bf16 v[70:73], v[212:215], v[166:169], v[70:73]
	v_mfma_f32_16x16x32_bf16 v[38:41], v[220:223], v[166:169], v[38:41]
	ds_read_b128 v[162:165], v229 offset:6144
	ds_read_b128 v[166:169], v230 offset:6144
	s_waitcnt lgkmcnt(2)
	v_mfma_f32_16x16x32_bf16 v[118:121], v[192:195], v[154:157], v[118:121]
	v_mfma_f32_16x16x32_bf16 v[90:93], v[200:203], v[154:157], v[90:93]
	v_mfma_f32_16x16x32_bf16 v[58:61], v[208:211], v[154:157], v[58:61]
	v_mfma_f32_16x16x32_bf16 v[26:29], v[216:219], v[154:157], v[26:29]
	v_mfma_f32_16x16x32_bf16 v[118:121], v[196:199], v[158:161], v[118:121]
	v_mfma_f32_16x16x32_bf16 v[90:93], v[204:207], v[158:161], v[90:93]
	v_mfma_f32_16x16x32_bf16 v[58:61], v[212:215], v[158:161], v[58:61]
	v_mfma_f32_16x16x32_bf16 v[26:29], v[220:223], v[158:161], v[26:29]
	ds_read_b128 v[154:157], v229 offset:8192
	ds_read_b128 v[158:161], v230 offset:8192
	s_waitcnt lgkmcnt(2)
	v_mfma_f32_16x16x32_bf16 v[110:113], v[192:195], v[162:165], v[110:113]
	v_mfma_f32_16x16x32_bf16 v[78:81], v[200:203], v[162:165], v[78:81]
	v_mfma_f32_16x16x32_bf16 v[46:49], v[208:211], v[162:165], v[46:49]
	v_mfma_f32_16x16x32_bf16 v[18:21], v[216:219], v[162:165], v[18:21]
	v_mfma_f32_16x16x32_bf16 v[110:113], v[196:199], v[166:169], v[110:113]
	v_mfma_f32_16x16x32_bf16 v[78:81], v[204:207], v[166:169], v[78:81]
	v_mfma_f32_16x16x32_bf16 v[46:49], v[212:215], v[166:169], v[46:49]
	v_mfma_f32_16x16x32_bf16 v[18:21], v[220:223], v[166:169], v[18:21]
	ds_read_b128 v[162:165], v229 offset:10240
	ds_read_b128 v[166:169], v230 offset:10240
	s_waitcnt lgkmcnt(2)
	v_mfma_f32_16x16x32_bf16 v[106:109], v[192:195], v[154:157], v[106:109]
	v_mfma_f32_16x16x32_bf16 v[74:77], v[200:203], v[154:157], v[74:77]
	v_mfma_f32_16x16x32_bf16 v[42:45], v[208:211], v[154:157], v[42:45]
	v_mfma_f32_16x16x32_bf16 v[14:17], v[216:219], v[154:157], v[14:17]
	v_mfma_f32_16x16x32_bf16 v[106:109], v[196:199], v[158:161], v[106:109]
	v_mfma_f32_16x16x32_bf16 v[74:77], v[204:207], v[158:161], v[74:77]
	v_mfma_f32_16x16x32_bf16 v[42:45], v[212:215], v[158:161], v[42:45]
	v_mfma_f32_16x16x32_bf16 v[14:17], v[220:223], v[158:161], v[14:17]
	ds_read_b128 v[154:157], v229 offset:12288
	ds_read_b128 v[158:161], v230 offset:12288
	s_waitcnt lgkmcnt(2)
	v_mfma_f32_16x16x32_bf16 v[98:101], v[192:195], v[162:165], v[98:101]
	v_mfma_f32_16x16x32_bf16 v[66:69], v[200:203], v[162:165], v[66:69]
	v_mfma_f32_16x16x32_bf16 v[34:37], v[208:211], v[162:165], v[34:37]
	v_mfma_f32_16x16x32_bf16 v[10:13], v[216:219], v[162:165], v[10:13]
	v_mfma_f32_16x16x32_bf16 v[98:101], v[196:199], v[166:169], v[98:101]
	v_mfma_f32_16x16x32_bf16 v[66:69], v[204:207], v[166:169], v[66:69]
	v_mfma_f32_16x16x32_bf16 v[34:37], v[212:215], v[166:169], v[34:37]
	v_mfma_f32_16x16x32_bf16 v[10:13], v[220:223], v[166:169], v[10:13]
	ds_read_b128 v[162:165], v229 offset:14336
	ds_read_b128 v[166:169], v230 offset:14336
	s_waitcnt lgkmcnt(2)
	v_mfma_f32_16x16x32_bf16 v[94:97], v[192:195], v[154:157], v[94:97]
	v_mfma_f32_16x16x32_bf16 v[62:65], v[200:203], v[154:157], v[62:65]
	v_mfma_f32_16x16x32_bf16 v[30:33], v[208:211], v[154:157], v[30:33]
	v_mfma_f32_16x16x32_bf16 v[6:9], v[216:219], v[154:157], v[6:9]
	v_mfma_f32_16x16x32_bf16 v[94:97], v[196:199], v[158:161], v[94:97]
	v_mfma_f32_16x16x32_bf16 v[62:65], v[204:207], v[158:161], v[62:65]
	v_mfma_f32_16x16x32_bf16 v[30:33], v[212:215], v[158:161], v[30:33]
	v_mfma_f32_16x16x32_bf16 v[6:9], v[220:223], v[158:161], v[6:9]
	s_waitcnt lgkmcnt(0)
	v_mfma_f32_16x16x32_bf16 v[82:85], v[192:195], v[162:165], v[82:85]
	v_mfma_f32_16x16x32_bf16 v[50:53], v[200:203], v[162:165], v[50:53]
	v_mfma_f32_16x16x32_bf16 v[22:25], v[208:211], v[162:165], v[22:25]
	v_mfma_f32_16x16x32_bf16 v[2:5], v[216:219], v[162:165], v[2:5]
	v_mfma_f32_16x16x32_bf16 v[82:85], v[196:199], v[166:169], v[82:85]
	v_mfma_f32_16x16x32_bf16 v[50:53], v[204:207], v[166:169], v[50:53]
	v_mfma_f32_16x16x32_bf16 v[22:25], v[212:215], v[166:169], v[22:25]
	v_mfma_f32_16x16x32_bf16 v[2:5], v[220:223], v[166:169], v[2:5]
	s_nop 7
	s_nop 7
	s_waitcnt vmcnt(6)
	v_add_u32_e32 v145, v149, v147
	s_waitcnt vmcnt(0)
	s_waitcnt lgkmcnt(0)
	s_lshl_b32 s16, s5, 7
	s_ashr_i32 s17, s16, 31
	s_lshl_b64 s[16:17], s[16:17], 1
	v_and_b32_e32 v1, 0xfffffc0, v1
	v_lshl_or_b32 v1, v143, 2, v1
	v_mul_lo_u32 v1, v1, s33
	v_lshl_or_b32 v1, v142, 2, v1
	s_lshl_b32 s18, s5, 1
	s_ashr_i32 s19, s18, 31
	s_lshl_b64 s[18:19], s[18:19], 2
	s_add_i32 s24, s24, 1
	v_mov_b64_e32 v[158:159], v[62:63]
	v_mov_b64_e32 v[160:161], v[64:65]
	v_mov_b64_e32 v[162:163], v[30:31]
	v_mov_b64_e32 v[164:165], v[32:33]
	v_mov_b64_e32 v[130:131], v[22:23]
	v_mov_b64_e32 v[132:133], v[24:25]
	s_waitcnt lgkmcnt(0)
	v_mov_b64_e32 v[224:225], v[38:39]
	v_mov_b64_e32 v[226:227], v[40:41]
	v_mov_b64_e32 v[38:39], v[34:35]
	v_mov_b64_e32 v[40:41], v[36:37]
	v_mov_b64_e32 v[34:35], v[2:3]
	v_mov_b64_e32 v[36:37], v[4:5]
	s_nop 2
	v_mov_b32_e32 v2, v170
	v_mov_b64_e32 v[208:209], v[114:115]
	v_mov_b64_e32 v[210:211], v[116:117]
	v_add_u32_e32 v2, s4, v2
	v_ashrrev_i32_e32 v3, 31, v2
	v_lshlrev_b64 v[2:3], 11, v[2:3]
	v_lshl_add_u64 v[2:3], s[8:9], 0, v[2:3]
	v_lshl_add_u64 v[2:3], v[2:3], 0, s[16:17]
	v_mov_b64_e32 v[212:213], v[54:55]
	v_mov_b64_e32 v[214:215], v[56:57]
	v_mov_b64_e32 v[216:217], v[122:123]
	v_mov_b64_e32 v[218:219], v[124:125]
	v_mov_b64_e32 v[220:221], v[102:103]
	v_mov_b64_e32 v[222:223], v[104:105]
	v_mov_b64_e32 v[228:229], v[118:119]
	v_mov_b64_e32 v[230:231], v[120:121]
	v_mov_b64_e32 v[232:233], v[58:59]
	v_mov_b64_e32 v[234:235], v[60:61]
	v_mov_b64_e32 v[236:237], v[26:27]
	v_mov_b64_e32 v[238:239], v[28:29]
	v_mov_b64_e32 v[240:241], v[110:111]
	v_mov_b64_e32 v[242:243], v[112:113]
	v_mov_b64_e32 v[244:245], v[78:79]
	v_mov_b64_e32 v[246:247], v[80:81]
	v_mov_b64_e32 v[248:249], v[46:47]
	v_mov_b64_e32 v[250:251], v[48:49]
	v_mov_b64_e32 v[62:63], v[106:107]
	v_mov_b64_e32 v[64:65], v[108:109]
	v_mov_b64_e32 v[46:47], v[74:75]
	v_mov_b64_e32 v[48:49], v[76:77]
	v_mov_b64_e32 v[74:75], v[98:99]
	v_mov_b64_e32 v[76:77], v[100:101]
	v_mov_b64_e32 v[54:55], v[66:67]
	v_mov_b64_e32 v[56:57], v[68:69]
	v_mov_b64_e32 v[58:59], v[158:159]
	v_mov_b64_e32 v[60:61], v[160:161]
	v_mov_b64_e32 v[66:67], v[50:51]
	v_mov_b64_e32 v[68:69], v[52:53]
	flat_load_dwordx4 v[138:141], v[2:3]
	flat_load_dwordx4 v[122:125], v[2:3] offset:16
	flat_load_dwordx4 v[118:121], v[2:3] offset:32
	flat_load_dwordx4 v[114:117], v[2:3] offset:48
	flat_load_dwordx4 v[110:113], v[2:3] offset:64
	flat_load_dwordx4 v[106:109], v[2:3] offset:80
	flat_load_dwordx4 v[102:105], v[2:3] offset:96
	flat_load_dwordx4 v[98:101], v[2:3] offset:112
	s_waitcnt vmcnt(0) lgkmcnt(0)
	s_barrier
	s_nop 7
	ds_write2_b32 v1, v126, v216 offset1:16
	ds_write2_b32 v1, v127, v217 offset0:68 offset1:84
	ds_write2_b32 v1, v128, v218 offset0:136 offset1:152
	ds_write2_b32 v1, v129, v219 offset0:204 offset1:220
	ds_write2_b32 v1, v228, v240 offset0:32 offset1:48
	ds_write2_b32 v1, v229, v241 offset0:100 offset1:116
	ds_write2_b32 v1, v230, v242 offset0:168 offset1:184
	ds_write2_b32 v1, v231, v243 offset0:236 offset1:252
	v_mov_b64_e32 v[180:181], v[18:19]
	v_mov_b64_e32 v[182:183], v[20:21]
	v_mov_b64_e32 v[78:79], v[94:95]
	v_mov_b64_e32 v[80:81], v[96:97]
	v_add_u32_e32 v135, 0x3000, v1
	v_add_u32_e32 v134, 0x3400, v1
	v_mov_b32_e32 v136, v170
	v_mov_b64_e32 v[50:51], v[130:131]
	v_mov_b64_e32 v[52:53], v[132:133]
	v_lshlrev_b32_e32 v137, 16, v138
	s_nop 1
	v_add_u32_e32 v130, 0x1000, v1
	v_add_u32_e32 v131, 0x1400, v1
	v_add_u32_e32 v132, 0x2000, v1
	v_add_u32_e32 v133, 0x2400, v1
	ds_write2_b32 v130, v208, v220 offset0:64 offset1:80
	ds_write2_b32 v130, v209, v221 offset0:132 offset1:148
	ds_write2_b32 v130, v210, v222 offset0:200 offset1:216
	ds_write2_b32 v131, v211, v223 offset0:12 offset1:28
	ds_write2_b32 v130, v90, v244 offset0:96 offset1:112
	ds_write2_b32 v130, v91, v245 offset0:164 offset1:180
	ds_write2_b32 v130, v92, v246 offset0:232 offset1:248
	ds_write2_b32 v131, v93, v247 offset0:44 offset1:60
	ds_write2_b32 v132, v86, v70 offset0:128 offset1:144
	ds_write2_b32 v132, v87, v71 offset0:196 offset1:212
	ds_write2_b32 v133, v88, v72 offset0:8 offset1:24
	ds_write2_b32 v133, v89, v73 offset0:76 offset1:92
	ds_write2_b32 v132, v232, v248 offset0:160 offset1:176
	ds_write2_b32 v132, v233, v249 offset0:228 offset1:244
	ds_write2_b32 v133, v234, v250 offset0:40 offset1:56
	ds_write2_b32 v133, v235, v251 offset0:108 offset1:124
	ds_write2_b32 v135, v212, v224 offset0:192 offset1:208
	ds_write2_b32 v134, v213, v225 offset0:4 offset1:20
	ds_write2_b32 v134, v214, v226 offset0:72 offset1:88
	ds_write2_b32 v134, v215, v227 offset0:140 offset1:156
	ds_write2_b32 v135, v236, v180 offset0:224 offset1:240
	ds_write2_b32 v134, v237, v181 offset0:36 offset1:52
	ds_write2_b32 v134, v238, v182 offset0:104 offset1:120
	ds_write2_b32 v134, v239, v183 offset0:172 offset1:188
	s_waitcnt lgkmcnt(0)
	s_barrier
	v_mov_b64_e32 v[30:31], v[42:43]
	v_mov_b64_e32 v[32:33], v[44:45]
	v_add_u32_e32 v126, s4, v136
	v_ashrrev_i32_e32 v127, 31, v126
	v_lshlrev_b64 v[2:3], 11, v[126:127]
	v_lshl_add_u64 v[2:3], s[8:9], 0, v[2:3]
	v_lshl_add_u64 v[128:129], v[2:3], 0, s[16:17]
	v_mul_lo_u32 v136, v136, s33
	v_mov_b64_e32 v[18:19], v[14:15]
	v_mov_b64_e32 v[20:21], v[16:17]
	v_and_b32_e32 v138, 0xffff0000, v138
	v_mov_b64_e32 v[22:23], v[10:11]
	v_mov_b64_e32 v[24:25], v[12:13]
	v_mov_b64_e32 v[42:43], v[162:163]
	v_mov_b64_e32 v[44:45], v[164:165]
	v_mov_b64_e32 v[26:27], v[6:7]
	v_mov_b64_e32 v[28:29], v[8:9]
	flat_load_dwordx4 v[94:97], v[128:129] offset:128
	flat_load_dwordx4 v[90:93], v[128:129] offset:144
	flat_load_dwordx4 v[86:89], v[128:129] offset:160
	flat_load_dwordx4 v[70:73], v[128:129] offset:176
	flat_load_dwordx4 v[14:17], v[128:129] offset:192
	flat_load_dwordx4 v[10:13], v[128:129] offset:208
	flat_load_dwordx4 v[6:9], v[128:129] offset:224
	flat_load_dwordx4 v[2:5], v[128:129] offset:240
	ds_read_b128 v[142:145], v136
	ds_read_b128 v[154:157], v136 offset:16
	s_waitcnt lgkmcnt(0)
	v_add_f32_e32 v137, v142, v137
	v_add_f32_e32 v138, v143, v138
	v_cvt_pk_bf16_f32 v138, v137, v138
	v_lshlrev_b32_e32 v137, 16, v139
	v_and_b32_e32 v139, 0xffff0000, v139
	v_add_f32_e32 v137, v144, v137
	v_add_f32_e32 v139, v145, v139
	v_cvt_pk_bf16_f32 v139, v137, v139
	v_lshlrev_b32_e32 v137, 16, v140
	v_and_b32_e32 v140, 0xffff0000, v140
	v_add_f32_e32 v137, v154, v137
	v_add_f32_e32 v140, v155, v140
	v_cvt_pk_bf16_f32 v140, v137, v140
	v_lshlrev_b32_e32 v137, 16, v141
	v_and_b32_e32 v141, 0xffff0000, v141
	v_add_f32_e32 v137, v156, v137
	v_add_f32_e32 v141, v157, v141
	v_and_b32_e32 v142, 0xffff0000, v138
	v_cvt_pk_bf16_f32 v141, v137, v141
	v_lshlrev_b32_e32 v137, 16, v138
	v_mul_f32_e32 v153, v142, v142
	v_lshlrev_b32_e32 v143, 16, v139
	v_fmac_f32_e32 v153, v137, v137
	v_and_b32_e32 v144, 0xffff0000, v139
	v_fmac_f32_e32 v153, v143, v143
	v_lshlrev_b32_e32 v145, 16, v140
	v_fmac_f32_e32 v153, v144, v144
	flat_store_dwordx4 v[128:129], v[138:141]
	v_and_b32_e32 v147, 0xffff0000, v140
	v_lshlrev_b32_e32 v149, 16, v141
	v_and_b32_e32 v151, 0xffff0000, v141
	v_fmac_f32_e32 v153, v145, v145
	ds_read_b128 v[138:141], v136 offset:32
	ds_read_b128 v[142:145], v136 offset:48
	v_lshlrev_b32_e32 v137, 16, v122
	v_and_b32_e32 v122, 0xffff0000, v122
	v_fmac_f32_e32 v153, v147, v147
	s_waitcnt lgkmcnt(0)
	v_add_f32_e32 v137, v138, v137
	v_add_f32_e32 v122, v139, v122
	v_cvt_pk_bf16_f32 v122, v137, v122
	v_lshlrev_b32_e32 v137, 16, v123
	v_and_b32_e32 v123, 0xffff0000, v123
	v_add_f32_e32 v137, v140, v137
	v_add_f32_e32 v123, v141, v123
	v_cvt_pk_bf16_f32 v123, v137, v123
	v_lshlrev_b32_e32 v137, 16, v124
	v_and_b32_e32 v124, 0xffff0000, v124
	v_add_f32_e32 v137, v142, v137
	v_add_f32_e32 v124, v143, v124
	v_cvt_pk_bf16_f32 v124, v137, v124
	v_lshlrev_b32_e32 v137, 16, v125
	v_and_b32_e32 v125, 0xffff0000, v125
	v_add_f32_e32 v137, v144, v137
	v_add_f32_e32 v125, v145, v125
	v_and_b32_e32 v138, 0xffff0000, v122
	v_cvt_pk_bf16_f32 v125, v137, v125
	v_lshlrev_b32_e32 v137, 16, v122
	v_mul_f32_e32 v138, v138, v138
	v_lshlrev_b32_e32 v139, 16, v123
	v_fmac_f32_e32 v138, v137, v137
	v_and_b32_e32 v140, 0xffff0000, v123
	v_fmac_f32_e32 v138, v139, v139
	v_lshlrev_b32_e32 v141, 16, v124
	v_fmac_f32_e32 v138, v140, v140
	v_and_b32_e32 v142, 0xffff0000, v124
	v_fmac_f32_e32 v138, v141, v141
	v_lshlrev_b32_e32 v143, 16, v125
	v_fmac_f32_e32 v138, v142, v142
	v_fmac_f32_e32 v153, v149, v149
	v_and_b32_e32 v144, 0xffff0000, v125
	v_fmac_f32_e32 v138, v143, v143
	v_fmac_f32_e32 v153, v151, v151
	v_fmac_f32_e32 v138, v144, v144
	flat_store_dwordx4 v[128:129], v[122:125] offset:16
	v_add_f32_e32 v137, v153, v138
	ds_read_b128 v[122:125], v136 offset:64
	ds_read_b128 v[138:141], v136 offset:80
	v_lshlrev_b32_e32 v142, 16, v118
	v_and_b32_e32 v118, 0xffff0000, v118
	s_waitcnt lgkmcnt(0)
	v_add_f32_e32 v122, v122, v142
	v_add_f32_e32 v118, v123, v118
	v_cvt_pk_bf16_f32 v118, v122, v118
	v_lshlrev_b32_e32 v122, 16, v119
	v_and_b32_e32 v119, 0xffff0000, v119
	v_add_f32_e32 v122, v124, v122
	v_add_f32_e32 v119, v125, v119
	v_cvt_pk_bf16_f32 v119, v122, v119
	v_lshlrev_b32_e32 v122, 16, v120
	v_and_b32_e32 v120, 0xffff0000, v120
	v_add_f32_e32 v122, v138, v122
	v_add_f32_e32 v120, v139, v120
	v_cvt_pk_bf16_f32 v120, v122, v120
	v_lshlrev_b32_e32 v122, 16, v121
	v_and_b32_e32 v121, 0xffff0000, v121
	v_add_f32_e32 v122, v140, v122
	v_add_f32_e32 v121, v141, v121
	v_and_b32_e32 v123, 0xffff0000, v118
	v_cvt_pk_bf16_f32 v121, v122, v121
	v_lshlrev_b32_e32 v122, 16, v118
	v_mul_f32_e32 v123, v123, v123
	v_lshlrev_b32_e32 v124, 16, v119
	v_fmac_f32_e32 v123, v122, v122
	v_and_b32_e32 v125, 0xffff0000, v119
	v_fmac_f32_e32 v123, v124, v124
	v_lshlrev_b32_e32 v138, 16, v120
	v_fmac_f32_e32 v123, v125, v125
	v_and_b32_e32 v139, 0xffff0000, v120
	v_fmac_f32_e32 v123, v138, v138
	v_lshlrev_b32_e32 v140, 16, v121
	v_fmac_f32_e32 v123, v139, v139
	v_and_b32_e32 v141, 0xffff0000, v121
	v_fmac_f32_e32 v123, v140, v140
	v_fmac_f32_e32 v123, v141, v141
	flat_store_dwordx4 v[128:129], v[118:121] offset:32
	v_add_f32_e32 v137, v137, v123
	ds_read_b128 v[118:121], v136 offset:96
	ds_read_b128 v[122:125], v136 offset:112
	v_lshlrev_b32_e32 v138, 16, v114
	v_and_b32_e32 v114, 0xffff0000, v114
	s_waitcnt lgkmcnt(0)
	v_add_f32_e32 v118, v118, v138
	v_add_f32_e32 v114, v119, v114
	v_cvt_pk_bf16_f32 v114, v118, v114
	v_lshlrev_b32_e32 v118, 16, v115
	v_and_b32_e32 v115, 0xffff0000, v115
	v_add_f32_e32 v118, v120, v118
	v_add_f32_e32 v115, v121, v115
	v_cvt_pk_bf16_f32 v115, v118, v115
	v_lshlrev_b32_e32 v118, 16, v116
	v_and_b32_e32 v116, 0xffff0000, v116
	v_add_f32_e32 v118, v122, v118
	v_add_f32_e32 v116, v123, v116
	v_cvt_pk_bf16_f32 v116, v118, v116
	v_lshlrev_b32_e32 v118, 16, v117
	v_and_b32_e32 v117, 0xffff0000, v117
	v_add_f32_e32 v118, v124, v118
	v_add_f32_e32 v117, v125, v117
	v_and_b32_e32 v119, 0xffff0000, v114
	v_cvt_pk_bf16_f32 v117, v118, v117
	v_lshlrev_b32_e32 v118, 16, v114
	v_mul_f32_e32 v119, v119, v119
	v_lshlrev_b32_e32 v120, 16, v115
	v_fmac_f32_e32 v119, v118, v118
	v_and_b32_e32 v121, 0xffff0000, v115
	v_fmac_f32_e32 v119, v120, v120
	v_lshlrev_b32_e32 v122, 16, v116
	v_fmac_f32_e32 v119, v121, v121
	v_and_b32_e32 v123, 0xffff0000, v116
	v_fmac_f32_e32 v119, v122, v122
	v_lshlrev_b32_e32 v124, 16, v117
	v_fmac_f32_e32 v119, v123, v123
	v_and_b32_e32 v125, 0xffff0000, v117
	v_fmac_f32_e32 v119, v124, v124
	v_fmac_f32_e32 v119, v125, v125
	flat_store_dwordx4 v[128:129], v[114:117] offset:48
	v_add_f32_e32 v122, v137, v119
	ds_read_b128 v[114:117], v136 offset:128
	ds_read_b128 v[118:121], v136 offset:144
	v_lshlrev_b32_e32 v123, 16, v110
	v_and_b32_e32 v110, 0xffff0000, v110
	s_waitcnt lgkmcnt(0)
	v_add_f32_e32 v114, v114, v123
	v_add_f32_e32 v110, v115, v110
	v_cvt_pk_bf16_f32 v110, v114, v110
	v_lshlrev_b32_e32 v114, 16, v111
	v_and_b32_e32 v111, 0xffff0000, v111
	v_add_f32_e32 v114, v116, v114
	v_add_f32_e32 v111, v117, v111
	v_cvt_pk_bf16_f32 v111, v114, v111
	v_lshlrev_b32_e32 v114, 16, v112
	v_and_b32_e32 v112, 0xffff0000, v112
	v_add_f32_e32 v114, v118, v114
	v_add_f32_e32 v112, v119, v112
	v_cvt_pk_bf16_f32 v112, v114, v112
	v_lshlrev_b32_e32 v114, 16, v113
	v_and_b32_e32 v113, 0xffff0000, v113
	v_add_f32_e32 v114, v120, v114
	v_add_f32_e32 v113, v121, v113
	v_and_b32_e32 v115, 0xffff0000, v110
	v_cvt_pk_bf16_f32 v113, v114, v113
	v_lshlrev_b32_e32 v114, 16, v110
	v_mul_f32_e32 v115, v115, v115
	v_lshlrev_b32_e32 v116, 16, v111
	v_fmac_f32_e32 v115, v114, v114
	v_and_b32_e32 v117, 0xffff0000, v111
	v_fmac_f32_e32 v115, v116, v116
	v_lshlrev_b32_e32 v118, 16, v112
	v_fmac_f32_e32 v115, v117, v117
	v_and_b32_e32 v119, 0xffff0000, v112
	v_fmac_f32_e32 v115, v118, v118
	v_lshlrev_b32_e32 v120, 16, v113
	v_fmac_f32_e32 v115, v119, v119
	v_and_b32_e32 v121, 0xffff0000, v113
	v_fmac_f32_e32 v115, v120, v120
	v_fmac_f32_e32 v115, v121, v121
	flat_store_dwordx4 v[128:129], v[110:113] offset:64
	v_add_f32_e32 v118, v122, v115
	ds_read_b128 v[110:113], v136 offset:160
	ds_read_b128 v[114:117], v136 offset:176
	v_lshlrev_b32_e32 v119, 16, v106
	v_and_b32_e32 v106, 0xffff0000, v106
	s_waitcnt lgkmcnt(0)
	v_add_f32_e32 v110, v110, v119
	v_add_f32_e32 v106, v111, v106
	v_cvt_pk_bf16_f32 v106, v110, v106
	v_lshlrev_b32_e32 v110, 16, v107
	v_and_b32_e32 v107, 0xffff0000, v107
	v_add_f32_e32 v110, v112, v110
	v_add_f32_e32 v107, v113, v107
	v_cvt_pk_bf16_f32 v107, v110, v107
	v_lshlrev_b32_e32 v110, 16, v108
	v_and_b32_e32 v108, 0xffff0000, v108
	v_add_f32_e32 v110, v114, v110
	v_add_f32_e32 v108, v115, v108
	v_cvt_pk_bf16_f32 v108, v110, v108
	v_lshlrev_b32_e32 v110, 16, v109
	v_and_b32_e32 v109, 0xffff0000, v109
	v_add_f32_e32 v110, v116, v110
	v_add_f32_e32 v109, v117, v109
	v_and_b32_e32 v111, 0xffff0000, v106
	v_cvt_pk_bf16_f32 v109, v110, v109
	v_lshlrev_b32_e32 v110, 16, v106
	v_mul_f32_e32 v111, v111, v111
	v_lshlrev_b32_e32 v112, 16, v107
	v_fmac_f32_e32 v111, v110, v110
	v_and_b32_e32 v113, 0xffff0000, v107
	v_fmac_f32_e32 v111, v112, v112
	v_lshlrev_b32_e32 v114, 16, v108
	v_fmac_f32_e32 v111, v113, v113
	v_and_b32_e32 v115, 0xffff0000, v108
	v_fmac_f32_e32 v111, v114, v114
	v_lshlrev_b32_e32 v116, 16, v109
	v_fmac_f32_e32 v111, v115, v115
	v_and_b32_e32 v117, 0xffff0000, v109
	v_fmac_f32_e32 v111, v116, v116
	v_fmac_f32_e32 v111, v117, v117
	flat_store_dwordx4 v[128:129], v[106:109] offset:80
	v_add_f32_e32 v114, v118, v111
	ds_read_b128 v[106:109], v136 offset:192
	ds_read_b128 v[110:113], v136 offset:208
	v_lshlrev_b32_e32 v115, 16, v102
	v_and_b32_e32 v102, 0xffff0000, v102
	s_waitcnt lgkmcnt(0)
	v_add_f32_e32 v106, v106, v115
	v_add_f32_e32 v102, v107, v102
	v_cvt_pk_bf16_f32 v102, v106, v102
	v_lshlrev_b32_e32 v106, 16, v103
	v_and_b32_e32 v103, 0xffff0000, v103
	v_add_f32_e32 v106, v108, v106
	v_add_f32_e32 v103, v109, v103
	v_cvt_pk_bf16_f32 v103, v106, v103
	v_lshlrev_b32_e32 v106, 16, v104
	v_and_b32_e32 v104, 0xffff0000, v104
	v_add_f32_e32 v106, v110, v106
	v_add_f32_e32 v104, v111, v104
	v_cvt_pk_bf16_f32 v104, v106, v104
	v_lshlrev_b32_e32 v106, 16, v105
	v_and_b32_e32 v105, 0xffff0000, v105
	v_add_f32_e32 v106, v112, v106
	v_add_f32_e32 v105, v113, v105
	v_and_b32_e32 v107, 0xffff0000, v102
	v_cvt_pk_bf16_f32 v105, v106, v105
	v_lshlrev_b32_e32 v106, 16, v102
	v_mul_f32_e32 v107, v107, v107
	v_lshlrev_b32_e32 v108, 16, v103
	v_fmac_f32_e32 v107, v106, v106
	v_and_b32_e32 v109, 0xffff0000, v103
	v_fmac_f32_e32 v107, v108, v108
	v_lshlrev_b32_e32 v110, 16, v104
	v_fmac_f32_e32 v107, v109, v109
	v_and_b32_e32 v111, 0xffff0000, v104
	v_fmac_f32_e32 v107, v110, v110
	v_lshlrev_b32_e32 v112, 16, v105
	v_fmac_f32_e32 v107, v111, v111
	v_and_b32_e32 v113, 0xffff0000, v105
	v_fmac_f32_e32 v107, v112, v112
	v_fmac_f32_e32 v107, v113, v113
	flat_store_dwordx4 v[128:129], v[102:105] offset:96
	v_add_f32_e32 v110, v114, v107
	ds_read_b128 v[102:105], v136 offset:224
	ds_read_b128 v[106:109], v136 offset:240
	v_lshlrev_b32_e32 v111, 16, v98
	v_and_b32_e32 v98, 0xffff0000, v98
	s_waitcnt lgkmcnt(0)
	v_add_f32_e32 v102, v102, v111
	v_add_f32_e32 v98, v103, v98
	v_cvt_pk_bf16_f32 v98, v102, v98
	v_lshlrev_b32_e32 v102, 16, v99
	v_and_b32_e32 v99, 0xffff0000, v99
	v_add_f32_e32 v102, v104, v102
	v_add_f32_e32 v99, v105, v99
	v_cvt_pk_bf16_f32 v99, v102, v99
	v_lshlrev_b32_e32 v102, 16, v100
	v_and_b32_e32 v100, 0xffff0000, v100
	v_add_f32_e32 v102, v106, v102
	v_add_f32_e32 v100, v107, v100
	v_cvt_pk_bf16_f32 v100, v102, v100
	v_lshlrev_b32_e32 v102, 16, v101
	v_and_b32_e32 v101, 0xffff0000, v101
	v_add_f32_e32 v102, v108, v102
	v_add_f32_e32 v101, v109, v101
	v_and_b32_e32 v103, 0xffff0000, v98
	v_cvt_pk_bf16_f32 v101, v102, v101
	v_lshlrev_b32_e32 v102, 16, v98
	v_mul_f32_e32 v103, v103, v103
	v_lshlrev_b32_e32 v104, 16, v99
	v_fmac_f32_e32 v103, v102, v102
	v_and_b32_e32 v105, 0xffff0000, v99
	v_fmac_f32_e32 v103, v104, v104
	v_lshlrev_b32_e32 v106, 16, v100
	v_fmac_f32_e32 v103, v105, v105
	v_and_b32_e32 v107, 0xffff0000, v100
	v_fmac_f32_e32 v103, v106, v106
	v_lshlrev_b32_e32 v108, 16, v101
	v_fmac_f32_e32 v103, v107, v107
	v_and_b32_e32 v109, 0xffff0000, v101
	v_fmac_f32_e32 v103, v108, v108
	flat_store_dwordx4 v[128:129], v[98:101] offset:112
	v_fmac_f32_e32 v103, v109, v109
	v_add_f32_e32 v102, v110, v103
	v_lshlrev_b64 v[98:99], 6, v[126:127]
	v_lshl_add_u64 v[98:99], s[6:7], 0, v[98:99]
	v_lshl_add_u64 v[98:99], v[98:99], 0, s[18:19]
	flat_store_dword v[98:99], v102
	s_waitcnt lgkmcnt(0)
	s_barrier
	ds_write2_b32 v1, v62, v74 offset1:16
	ds_write2_b32 v1, v63, v75 offset0:68 offset1:84
	ds_write2_b32 v1, v64, v76 offset0:136 offset1:152
	ds_write2_b32 v1, v65, v77 offset0:204 offset1:220
	ds_write2_b32 v1, v78, v82 offset0:32 offset1:48
	ds_write2_b32 v1, v79, v83 offset0:100 offset1:116
	ds_write2_b32 v1, v80, v84 offset0:168 offset1:184
	ds_write2_b32 v1, v81, v85 offset0:236 offset1:252
	ds_write2_b32 v130, v46, v54 offset0:64 offset1:80
	ds_write2_b32 v130, v47, v55 offset0:132 offset1:148
	ds_write2_b32 v130, v48, v56 offset0:200 offset1:216
	ds_write2_b32 v131, v49, v57 offset0:12 offset1:28
	ds_write2_b32 v130, v58, v66 offset0:96 offset1:112
	ds_write2_b32 v130, v59, v67 offset0:164 offset1:180
	ds_write2_b32 v130, v60, v68 offset0:232 offset1:248
	ds_write2_b32 v131, v61, v69 offset0:44 offset1:60
	ds_write2_b32 v132, v30, v38 offset0:128 offset1:144
	ds_write2_b32 v132, v31, v39 offset0:196 offset1:212
	ds_write2_b32 v133, v32, v40 offset0:8 offset1:24
	ds_write2_b32 v133, v33, v41 offset0:76 offset1:92
	ds_write2_b32 v132, v42, v50 offset0:160 offset1:176
	ds_write2_b32 v132, v43, v51 offset0:228 offset1:244
	ds_write2_b32 v133, v44, v52 offset0:40 offset1:56
	ds_write2_b32 v133, v45, v53 offset0:108 offset1:124
	ds_write2_b32 v135, v18, v22 offset0:192 offset1:208
	ds_write2_b32 v134, v19, v23 offset0:4 offset1:20
	ds_write2_b32 v134, v20, v24 offset0:72 offset1:88
	ds_write2_b32 v134, v21, v25 offset0:140 offset1:156
	ds_write2_b32 v135, v26, v34 offset0:224 offset1:240
	ds_write2_b32 v134, v27, v35 offset0:36 offset1:52
	ds_write2_b32 v134, v28, v36 offset0:104 offset1:120
	ds_write2_b32 v134, v29, v37 offset0:172 offset1:188
	v_mov_b32_e32 v1, v170
	s_waitcnt lgkmcnt(0)
	s_barrier
	s_waitcnt vmcnt(0)
	v_lshlrev_b32_e32 v28, 16, v94
	v_add_u32_e32 v18, s4, v1
	v_ashrrev_i32_e32 v19, 31, v18
	v_lshlrev_b64 v[20:21], 11, v[18:19]
	v_lshl_add_u64 v[20:21], s[38:39], 0, v[20:21]
	v_mul_lo_u32 v1, v1, s33
	v_lshl_add_u64 v[32:33], v[20:21], 0, s[16:17]
	ds_read_b128 v[20:23], v1
	ds_read_b128 v[24:27], v1 offset:16
	s_mov_b64 s[4:5], 0
	s_waitcnt lgkmcnt(1)
	v_add_f32_e32 v20, v20, v28
	v_and_b32_e32 v28, 0xffff0000, v94
	v_add_f32_e32 v21, v21, v28
	v_cvt_pk_bf16_f32 v28, v20, v21
	v_and_b32_e32 v21, 0xffff0000, v95
	v_lshlrev_b32_e32 v20, 16, v95
	v_add_f32_e32 v21, v23, v21
	v_add_f32_e32 v20, v22, v20
	v_cvt_pk_bf16_f32 v29, v20, v21
	v_and_b32_e32 v21, 0xffff0000, v96
	v_lshlrev_b32_e32 v20, 16, v96
	s_waitcnt lgkmcnt(0)
	v_add_f32_e32 v21, v25, v21
	v_add_f32_e32 v20, v24, v20
	v_cvt_pk_bf16_f32 v30, v20, v21
	v_and_b32_e32 v21, 0xffff0000, v97
	v_lshlrev_b32_e32 v20, 16, v97
	v_add_f32_e32 v21, v27, v21
	v_add_f32_e32 v20, v26, v20
	v_cvt_pk_bf16_f32 v31, v20, v21
	v_and_b32_e32 v21, 0xffff0000, v28
	v_lshlrev_b32_e32 v20, 16, v28
	v_mul_f32_e32 v34, v21, v21
	v_lshlrev_b32_e32 v22, 16, v29
	v_fmac_f32_e32 v34, v20, v20
	v_and_b32_e32 v23, 0xffff0000, v29
	v_fmac_f32_e32 v34, v22, v22
	v_lshlrev_b32_e32 v24, 16, v30
	v_fmac_f32_e32 v34, v23, v23
	v_and_b32_e32 v25, 0xffff0000, v30
	v_fmac_f32_e32 v34, v24, v24
	v_add_co_u32_e32 v20, vcc, s90, v32
	v_lshlrev_b32_e32 v26, 16, v31
	v_fmac_f32_e32 v34, v25, v25
	v_addc_co_u32_e32 v21, vcc, 0, v33, vcc
	v_and_b32_e32 v27, 0xffff0000, v31
	v_fmac_f32_e32 v34, v26, v26
	flat_store_dwordx4 v[20:21], v[28:31] offset:128
	v_fmac_f32_e32 v34, v27, v27
	ds_read_b128 v[22:25], v1 offset:32
	ds_read_b128 v[26:29], v1 offset:48
	v_lshlrev_b32_e32 v30, 16, v90
	s_waitcnt lgkmcnt(0)
	v_add_f32_e32 v22, v22, v30
	v_and_b32_e32 v30, 0xffff0000, v90
	v_add_f32_e32 v23, v23, v30
	v_cvt_pk_bf16_f32 v22, v22, v23
	v_lshlrev_b32_e32 v23, 16, v91
	v_add_f32_e32 v23, v24, v23
	v_and_b32_e32 v24, 0xffff0000, v91
	v_add_f32_e32 v24, v25, v24
	v_cvt_pk_bf16_f32 v23, v23, v24
	v_lshlrev_b32_e32 v24, 16, v92
	v_and_b32_e32 v25, 0xffff0000, v92
	v_add_f32_e32 v24, v26, v24
	v_add_f32_e32 v25, v27, v25
	v_cvt_pk_bf16_f32 v24, v24, v25
	v_lshlrev_b32_e32 v25, 16, v93
	v_and_b32_e32 v26, 0xffff0000, v93
	v_add_f32_e32 v25, v28, v25
	v_add_f32_e32 v26, v29, v26
	v_and_b32_e32 v27, 0xffff0000, v22
	v_cvt_pk_bf16_f32 v25, v25, v26
	v_lshlrev_b32_e32 v26, 16, v22
	v_mul_f32_e32 v27, v27, v27
	v_lshlrev_b32_e32 v28, 16, v23
	v_fmac_f32_e32 v27, v26, v26
	v_and_b32_e32 v29, 0xffff0000, v23
	v_fmac_f32_e32 v27, v28, v28
	v_lshlrev_b32_e32 v30, 16, v24
	v_fmac_f32_e32 v27, v29, v29
	v_and_b32_e32 v31, 0xffff0000, v24
	v_fmac_f32_e32 v27, v30, v30
	v_lshlrev_b32_e32 v32, 16, v25
	v_fmac_f32_e32 v27, v31, v31
	v_and_b32_e32 v33, 0xffff0000, v25
	v_fmac_f32_e32 v27, v32, v32
	v_fmac_f32_e32 v27, v33, v33
	flat_store_dwordx4 v[20:21], v[22:25] offset:144
	v_add_f32_e32 v30, v34, v27
	ds_read_b128 v[22:25], v1 offset:64
	ds_read_b128 v[26:29], v1 offset:80
	v_lshlrev_b32_e32 v31, 16, v86
	s_waitcnt lgkmcnt(0)
	v_add_f32_e32 v22, v22, v31
	v_and_b32_e32 v31, 0xffff0000, v86
	v_add_f32_e32 v23, v23, v31
	v_cvt_pk_bf16_f32 v22, v22, v23
	v_lshlrev_b32_e32 v23, 16, v87
	v_add_f32_e32 v23, v24, v23
	v_and_b32_e32 v24, 0xffff0000, v87
	v_add_f32_e32 v24, v25, v24
	v_cvt_pk_bf16_f32 v23, v23, v24
	v_lshlrev_b32_e32 v24, 16, v88
	v_and_b32_e32 v25, 0xffff0000, v88
	v_add_f32_e32 v24, v26, v24
	v_add_f32_e32 v25, v27, v25
	v_cvt_pk_bf16_f32 v24, v24, v25
	v_lshlrev_b32_e32 v25, 16, v89
	v_and_b32_e32 v26, 0xffff0000, v89
	v_add_f32_e32 v25, v28, v25
	v_add_f32_e32 v26, v29, v26
	v_and_b32_e32 v27, 0xffff0000, v22
	v_cvt_pk_bf16_f32 v25, v25, v26
	v_lshlrev_b32_e32 v26, 16, v22
	v_mul_f32_e32 v27, v27, v27
	v_lshlrev_b32_e32 v28, 16, v23
	v_fmac_f32_e32 v27, v26, v26
	v_and_b32_e32 v29, 0xffff0000, v23
	v_fmac_f32_e32 v27, v28, v28
	v_lshlrev_b32_e32 v31, 16, v24
	v_fmac_f32_e32 v27, v29, v29
	v_and_b32_e32 v32, 0xffff0000, v24
	v_fmac_f32_e32 v27, v31, v31
	v_lshlrev_b32_e32 v33, 16, v25
	v_fmac_f32_e32 v27, v32, v32
	v_and_b32_e32 v34, 0xffff0000, v25
	v_fmac_f32_e32 v27, v33, v33
	v_fmac_f32_e32 v27, v34, v34
	flat_store_dwordx4 v[20:21], v[22:25] offset:160
	v_add_f32_e32 v30, v30, v27
	ds_read_b128 v[22:25], v1 offset:96
	ds_read_b128 v[26:29], v1 offset:112
	v_lshlrev_b32_e32 v31, 16, v70
	s_waitcnt lgkmcnt(0)
	v_add_f32_e32 v22, v22, v31
	v_and_b32_e32 v31, 0xffff0000, v70
	v_add_f32_e32 v23, v23, v31
	v_cvt_pk_bf16_f32 v22, v22, v23
	v_lshlrev_b32_e32 v23, 16, v71
	v_add_f32_e32 v23, v24, v23
	v_and_b32_e32 v24, 0xffff0000, v71
	v_add_f32_e32 v24, v25, v24
	v_cvt_pk_bf16_f32 v23, v23, v24
	v_lshlrev_b32_e32 v24, 16, v72
	v_and_b32_e32 v25, 0xffff0000, v72
	v_add_f32_e32 v24, v26, v24
	v_add_f32_e32 v25, v27, v25
	v_cvt_pk_bf16_f32 v24, v24, v25
	v_lshlrev_b32_e32 v25, 16, v73
	v_and_b32_e32 v26, 0xffff0000, v73
	v_add_f32_e32 v25, v28, v25
	v_add_f32_e32 v26, v29, v26
	v_and_b32_e32 v27, 0xffff0000, v22
	v_cvt_pk_bf16_f32 v25, v25, v26
	v_lshlrev_b32_e32 v26, 16, v22
	v_mul_f32_e32 v27, v27, v27
	v_lshlrev_b32_e32 v28, 16, v23
	v_fmac_f32_e32 v27, v26, v26
	v_and_b32_e32 v29, 0xffff0000, v23
	v_fmac_f32_e32 v27, v28, v28
	v_lshlrev_b32_e32 v31, 16, v24
	v_fmac_f32_e32 v27, v29, v29
	v_and_b32_e32 v32, 0xffff0000, v24
	v_fmac_f32_e32 v27, v31, v31
	v_lshlrev_b32_e32 v33, 16, v25
	v_fmac_f32_e32 v27, v32, v32
	v_and_b32_e32 v34, 0xffff0000, v25
	v_fmac_f32_e32 v27, v33, v33
	v_fmac_f32_e32 v27, v34, v34
	flat_store_dwordx4 v[20:21], v[22:25] offset:176
	v_add_f32_e32 v30, v30, v27
	ds_read_b128 v[22:25], v1 offset:128
	ds_read_b128 v[26:29], v1 offset:144
	v_lshlrev_b32_e32 v31, 16, v14
	v_and_b32_e32 v14, 0xffff0000, v14
	s_waitcnt lgkmcnt(0)
	v_add_f32_e32 v22, v22, v31
	v_add_f32_e32 v14, v23, v14
	v_cvt_pk_bf16_f32 v14, v22, v14
	v_lshlrev_b32_e32 v22, 16, v15
	v_and_b32_e32 v15, 0xffff0000, v15
	v_add_f32_e32 v22, v24, v22
	v_add_f32_e32 v15, v25, v15
	v_cvt_pk_bf16_f32 v15, v22, v15
	v_lshlrev_b32_e32 v22, 16, v16
	v_and_b32_e32 v16, 0xffff0000, v16
	v_add_f32_e32 v22, v26, v22
	v_add_f32_e32 v16, v27, v16
	v_cvt_pk_bf16_f32 v16, v22, v16
	v_lshlrev_b32_e32 v22, 16, v17
	v_and_b32_e32 v17, 0xffff0000, v17
	v_add_f32_e32 v22, v28, v22
	v_add_f32_e32 v17, v29, v17
	v_and_b32_e32 v23, 0xffff0000, v14
	v_cvt_pk_bf16_f32 v17, v22, v17
	v_lshlrev_b32_e32 v22, 16, v14
	v_mul_f32_e32 v23, v23, v23
	v_lshlrev_b32_e32 v24, 16, v15
	v_fmac_f32_e32 v23, v22, v22
	v_and_b32_e32 v25, 0xffff0000, v15
	v_fmac_f32_e32 v23, v24, v24
	v_lshlrev_b32_e32 v26, 16, v16
	v_fmac_f32_e32 v23, v25, v25
	v_and_b32_e32 v27, 0xffff0000, v16
	v_fmac_f32_e32 v23, v26, v26
	v_lshlrev_b32_e32 v28, 16, v17
	v_fmac_f32_e32 v23, v27, v27
	v_and_b32_e32 v29, 0xffff0000, v17
	v_fmac_f32_e32 v23, v28, v28
	v_fmac_f32_e32 v23, v29, v29
	flat_store_dwordx4 v[20:21], v[14:17] offset:192
	v_add_f32_e32 v26, v30, v23
	ds_read_b128 v[14:17], v1 offset:160
	ds_read_b128 v[22:25], v1 offset:176
	v_lshlrev_b32_e32 v27, 16, v10
	v_and_b32_e32 v10, 0xffff0000, v10
	s_waitcnt lgkmcnt(0)
	v_add_f32_e32 v14, v14, v27
	v_add_f32_e32 v10, v15, v10
	v_cvt_pk_bf16_f32 v10, v14, v10
	v_lshlrev_b32_e32 v14, 16, v11
	v_and_b32_e32 v11, 0xffff0000, v11
	v_add_f32_e32 v14, v16, v14
	v_add_f32_e32 v11, v17, v11
	v_cvt_pk_bf16_f32 v11, v14, v11
	v_lshlrev_b32_e32 v14, 16, v12
	v_and_b32_e32 v12, 0xffff0000, v12
	v_add_f32_e32 v14, v22, v14
	v_add_f32_e32 v12, v23, v12
	v_cvt_pk_bf16_f32 v12, v14, v12
	v_lshlrev_b32_e32 v14, 16, v13
	v_and_b32_e32 v13, 0xffff0000, v13
	v_add_f32_e32 v14, v24, v14
	v_add_f32_e32 v13, v25, v13
	v_and_b32_e32 v15, 0xffff0000, v10
	v_cvt_pk_bf16_f32 v13, v14, v13
	v_lshlrev_b32_e32 v14, 16, v10
	v_mul_f32_e32 v15, v15, v15
	v_lshlrev_b32_e32 v16, 16, v11
	v_fmac_f32_e32 v15, v14, v14
	v_and_b32_e32 v17, 0xffff0000, v11
	v_fmac_f32_e32 v15, v16, v16
	v_lshlrev_b32_e32 v22, 16, v12
	v_fmac_f32_e32 v15, v17, v17
	v_and_b32_e32 v23, 0xffff0000, v12
	v_fmac_f32_e32 v15, v22, v22
	v_lshlrev_b32_e32 v24, 16, v13
	v_fmac_f32_e32 v15, v23, v23
	v_and_b32_e32 v25, 0xffff0000, v13
	v_fmac_f32_e32 v15, v24, v24
	v_fmac_f32_e32 v15, v25, v25
	flat_store_dwordx4 v[20:21], v[10:13] offset:208
	v_add_f32_e32 v22, v26, v15
	ds_read_b128 v[10:13], v1 offset:192
	ds_read_b128 v[14:17], v1 offset:208
	v_lshlrev_b32_e32 v23, 16, v6
	v_and_b32_e32 v6, 0xffff0000, v6
	s_waitcnt lgkmcnt(0)
	v_add_f32_e32 v10, v10, v23
	v_add_f32_e32 v6, v11, v6
	v_cvt_pk_bf16_f32 v6, v10, v6
	v_lshlrev_b32_e32 v10, 16, v7
	v_and_b32_e32 v7, 0xffff0000, v7
	v_add_f32_e32 v10, v12, v10
	v_add_f32_e32 v7, v13, v7
	v_cvt_pk_bf16_f32 v7, v10, v7
	v_lshlrev_b32_e32 v10, 16, v8
	v_and_b32_e32 v8, 0xffff0000, v8
	v_add_f32_e32 v10, v14, v10
	v_add_f32_e32 v8, v15, v8
	v_cvt_pk_bf16_f32 v8, v10, v8
	v_lshlrev_b32_e32 v10, 16, v9
	v_and_b32_e32 v9, 0xffff0000, v9
	v_add_f32_e32 v10, v16, v10
	v_add_f32_e32 v9, v17, v9
	v_and_b32_e32 v11, 0xffff0000, v6
	v_cvt_pk_bf16_f32 v9, v10, v9
	v_lshlrev_b32_e32 v10, 16, v6
	v_mul_f32_e32 v11, v11, v11
	v_lshlrev_b32_e32 v12, 16, v7
	v_fmac_f32_e32 v11, v10, v10
	v_and_b32_e32 v13, 0xffff0000, v7
	v_fmac_f32_e32 v11, v12, v12
	v_lshlrev_b32_e32 v14, 16, v8
	v_fmac_f32_e32 v11, v13, v13
	v_and_b32_e32 v15, 0xffff0000, v8
	v_fmac_f32_e32 v11, v14, v14
	v_lshlrev_b32_e32 v16, 16, v9
	v_fmac_f32_e32 v11, v15, v15
	v_and_b32_e32 v17, 0xffff0000, v9
	v_fmac_f32_e32 v11, v16, v16
	v_fmac_f32_e32 v11, v17, v17
	flat_store_dwordx4 v[20:21], v[6:9] offset:224
	v_add_f32_e32 v14, v22, v11
	ds_read_b128 v[6:9], v1 offset:224
	ds_read_b128 v[10:13], v1 offset:240
	v_lshlrev_b32_e32 v1, 16, v2
	v_and_b32_e32 v2, 0xffff0000, v2
	s_waitcnt lgkmcnt(0)
	v_add_f32_e32 v1, v6, v1
	v_add_f32_e32 v2, v7, v2
	v_cvt_pk_bf16_f32 v2, v1, v2
	v_lshlrev_b32_e32 v1, 16, v3
	v_and_b32_e32 v3, 0xffff0000, v3
	v_add_f32_e32 v1, v8, v1
	v_add_f32_e32 v3, v9, v3
	v_cvt_pk_bf16_f32 v3, v1, v3
	v_lshlrev_b32_e32 v1, 16, v4
	v_and_b32_e32 v4, 0xffff0000, v4
	v_add_f32_e32 v1, v10, v1
	v_add_f32_e32 v4, v11, v4
	v_cvt_pk_bf16_f32 v4, v1, v4
	v_lshlrev_b32_e32 v1, 16, v5
	v_and_b32_e32 v5, 0xffff0000, v5
	v_add_f32_e32 v1, v12, v1
	v_add_f32_e32 v5, v13, v5
	v_and_b32_e32 v6, 0xffff0000, v2
	v_cvt_pk_bf16_f32 v5, v1, v5
	v_lshlrev_b32_e32 v1, 16, v2
	v_mul_f32_e32 v6, v6, v6
	v_lshlrev_b32_e32 v7, 16, v3
	v_fmac_f32_e32 v6, v1, v1
	v_and_b32_e32 v8, 0xffff0000, v3
	v_fmac_f32_e32 v6, v7, v7
	v_lshlrev_b32_e32 v9, 16, v4
	v_fmac_f32_e32 v6, v8, v8
	v_and_b32_e32 v10, 0xffff0000, v4
	v_fmac_f32_e32 v6, v9, v9
	v_lshlrev_b32_e32 v11, 16, v5
	v_fmac_f32_e32 v6, v10, v10
	v_and_b32_e32 v12, 0xffff0000, v5
	v_fmac_f32_e32 v6, v11, v11
	flat_store_dwordx4 v[20:21], v[2:5] offset:240
	v_fmac_f32_e32 v6, v12, v12
	v_add_f32_e32 v1, v14, v6
	v_lshlrev_b64 v[2:3], 6, v[18:19]
	v_lshl_add_u64 v[2:3], s[6:7], 0, v[2:3]
	v_lshl_add_u64 v[2:3], v[2:3], 0, s[18:19]
	flat_store_dword v[2:3], v1 offset:4
	s_branch .LBB0_342

.Lbk64_418:
	s_waitcnt vmcnt(0)
	s_barrier
	ds_read_b128 v[192:195], v227
	ds_read_b128 v[196:199], v228
	ds_read_b128 v[200:203], v227 offset:2048
	ds_read_b128 v[204:207], v228 offset:2048
	ds_read_b128 v[208:211], v227 offset:4096
	ds_read_b128 v[212:215], v228 offset:4096
	ds_read_b128 v[216:219], v227 offset:6144
	ds_read_b128 v[220:223], v228 offset:6144
	s_add_u32 s4, s4, 0x80
	s_addc_u32 s5, s5, 0
	s_add_u32 s22, s22, 0x80
	s_addc_u32 s23, s23, 0
	s_waitcnt lgkmcnt(0)
	ds_read_b128 v[154:157], v229 offset:0
	ds_read_b128 v[158:161], v230 offset:0
	ds_read_b128 v[162:165], v229 offset:2048
	ds_read_b128 v[166:169], v230 offset:2048
	s_waitcnt lgkmcnt(2)
	v_mfma_f32_16x16x32_bf16 v[126:129], v[192:195], v[154:157], v[126:129]
	v_mfma_f32_16x16x32_bf16 v[114:117], v[200:203], v[154:157], v[114:117]
	v_mfma_f32_16x16x32_bf16 v[94:97], v[208:211], v[154:157], v[94:97]
	v_mfma_f32_16x16x32_bf16 v[62:65], v[216:219], v[154:157], v[62:65]
	v_readfirstlane_b32 s32, v142
	s_lshl_b32 m0, s32, 3
	v_add_u32_e32 v226, 0, v224
	v_max_i32_e32 v226, 0, v226
	v_min_i32_e32 v226, 0xffff, v226
	v_lshl_add_u32 v226, v226, 11, v231
	global_load_lds_dwordx4 v226, s[4:5]
	v_mfma_f32_16x16x32_bf16 v[126:129], v[196:199], v[158:161], v[126:129]
	v_mfma_f32_16x16x32_bf16 v[114:117], v[204:207], v[158:161], v[114:117]
	v_mfma_f32_16x16x32_bf16 v[94:97], v[212:215], v[158:161], v[94:97]
	v_mfma_f32_16x16x32_bf16 v[62:65], v[220:223], v[158:161], v[62:65]
	s_add_u32 m0, m0, 0x400
	v_add_u32_e32 v226, 8, v224
	v_max_i32_e32 v226, 0, v226
	v_min_i32_e32 v226, 0xffff, v226
	v_lshl_add_u32 v226, v226, 11, v231
	global_load_lds_dwordx4 v226, s[4:5]
	ds_read_b128 v[154:157], v229 offset:4096
	ds_read_b128 v[158:161], v230 offset:4096
	s_waitcnt lgkmcnt(2)
	v_mfma_f32_16x16x32_bf16 v[122:125], v[192:195], v[162:165], v[122:125]
	v_mfma_f32_16x16x32_bf16 v[106:109], v[200:203], v[162:165], v[106:109]
	v_mfma_f32_16x16x32_bf16 v[78:81], v[208:211], v[162:165], v[78:81]
	v_mfma_f32_16x16x32_bf16 v[46:49], v[216:219], v[162:165], v[46:49]
	s_add_u32 m0, m0, 0x400
	v_add_u32_e32 v226, 16, v224
	v_max_i32_e32 v226, 0, v226
	v_min_i32_e32 v226, 0xffff, v226
	v_lshl_add_u32 v226, v226, 11, v231
	global_load_lds_dwordx4 v226, s[4:5]
	v_mfma_f32_16x16x32_bf16 v[122:125], v[196:199], v[166:169], v[122:125]
	v_mfma_f32_16x16x32_bf16 v[106:109], v[204:207], v[166:169], v[106:109]
	v_mfma_f32_16x16x32_bf16 v[78:81], v[212:215], v[166:169], v[78:81]
	v_mfma_f32_16x16x32_bf16 v[46:49], v[220:223], v[166:169], v[46:49]
	s_add_u32 m0, m0, 0x400
	v_add_u32_e32 v226, 24, v224
	v_max_i32_e32 v226, 0, v226
	v_min_i32_e32 v226, 0xffff, v226
	v_lshl_add_u32 v226, v226, 11, v231
	global_load_lds_dwordx4 v226, s[4:5]
	ds_read_b128 v[162:165], v229 offset:6144
	ds_read_b128 v[166:169], v230 offset:6144
	s_waitcnt lgkmcnt(2)
	v_mfma_f32_16x16x32_bf16 v[118:121], v[192:195], v[154:157], v[118:121]
	v_mfma_f32_16x16x32_bf16 v[98:101], v[200:203], v[154:157], v[98:101]
	v_mfma_f32_16x16x32_bf16 v[70:73], v[208:211], v[154:157], v[70:73]
	v_mfma_f32_16x16x32_bf16 v[38:41], v[216:219], v[154:157], v[38:41]
	s_add_u32 m0, m0, 0x400
	v_add_u32_e32 v226, 32, v224
	v_max_i32_e32 v226, 0, v226
	v_min_i32_e32 v226, 0xffff, v226
	v_lshl_add_u32 v226, v226, 11, v231
	global_load_lds_dwordx4 v226, s[4:5]
	v_mfma_f32_16x16x32_bf16 v[118:121], v[196:199], v[158:161], v[118:121]
	v_mfma_f32_16x16x32_bf16 v[98:101], v[204:207], v[158:161], v[98:101]
	v_mfma_f32_16x16x32_bf16 v[70:73], v[212:215], v[158:161], v[70:73]
	v_mfma_f32_16x16x32_bf16 v[38:41], v[220:223], v[158:161], v[38:41]
	s_add_u32 m0, m0, 0x400
	v_add_u32_e32 v226, 40, v224
	v_max_i32_e32 v226, 0, v226
	v_min_i32_e32 v226, 0xffff, v226
	v_lshl_add_u32 v226, v226, 11, v231
	global_load_lds_dwordx4 v226, s[4:5]
	ds_read_b128 v[154:157], v229 offset:8192
	ds_read_b128 v[158:161], v230 offset:8192
	s_waitcnt lgkmcnt(2)
	v_mfma_f32_16x16x32_bf16 v[110:113], v[192:195], v[162:165], v[110:113]
	v_mfma_f32_16x16x32_bf16 v[86:89], v[200:203], v[162:165], v[86:89]
	v_mfma_f32_16x16x32_bf16 v[54:57], v[208:211], v[162:165], v[54:57]
	v_mfma_f32_16x16x32_bf16 v[26:29], v[216:219], v[162:165], v[26:29]
	s_add_u32 m0, m0, 0x400
	v_add_u32_e32 v226, 48, v224
	v_max_i32_e32 v226, 0, v226
	v_min_i32_e32 v226, 0xffff, v226
	v_lshl_add_u32 v226, v226, 11, v231
	global_load_lds_dwordx4 v226, s[4:5]
	v_mfma_f32_16x16x32_bf16 v[110:113], v[196:199], v[166:169], v[110:113]
	v_mfma_f32_16x16x32_bf16 v[86:89], v[204:207], v[166:169], v[86:89]
	v_mfma_f32_16x16x32_bf16 v[54:57], v[212:215], v[166:169], v[54:57]
	v_mfma_f32_16x16x32_bf16 v[26:29], v[220:223], v[166:169], v[26:29]
	s_add_u32 m0, m0, 0x400
	v_add_u32_e32 v226, 56, v224
	v_max_i32_e32 v226, 0, v226
	v_min_i32_e32 v226, 0xffff, v226
	v_lshl_add_u32 v226, v226, 11, v231
	global_load_lds_dwordx4 v226, s[4:5]
	ds_read_b128 v[162:165], v229 offset:10240
	ds_read_b128 v[166:169], v230 offset:10240
	s_waitcnt lgkmcnt(2)
	v_mfma_f32_16x16x32_bf16 v[102:105], v[192:195], v[154:157], v[102:105]
	v_mfma_f32_16x16x32_bf16 v[74:77], v[200:203], v[154:157], v[74:77]
	v_mfma_f32_16x16x32_bf16 v[42:45], v[208:211], v[154:157], v[42:45]
	v_mfma_f32_16x16x32_bf16 v[18:21], v[216:219], v[154:157], v[18:21]
	s_add_u32 m0, s21, 17
	s_and_b32 m0, m0, 1
	s_lshl_b32 m0, m0, 14
	s_add_u32 m0, m0, 0x8000
	v_readfirstlane_b32 s32, v142
	s_lshl_b32 s32, s32, 2
	s_add_u32 m0, m0, s32
	v_mov_b32_e32 v226, v225
	global_load_lds_dwordx4 v226, s[22:23]
	v_mfma_f32_16x16x32_bf16 v[102:105], v[196:199], v[158:161], v[102:105]
	v_mfma_f32_16x16x32_bf16 v[74:77], v[204:207], v[158:161], v[74:77]
	v_mfma_f32_16x16x32_bf16 v[42:45], v[212:215], v[158:161], v[42:45]
	v_mfma_f32_16x16x32_bf16 v[18:21], v[220:223], v[158:161], v[18:21]
	s_add_u32 m0, m0, 0x400
	v_add_u32_e32 v226, 0x4000, v225
	global_load_lds_dwordx4 v226, s[22:23]
	ds_read_b128 v[154:157], v229 offset:12288
	ds_read_b128 v[158:161], v230 offset:12288
	s_waitcnt lgkmcnt(2)
	v_mfma_f32_16x16x32_bf16 v[90:93], v[192:195], v[162:165], v[90:93]
	v_mfma_f32_16x16x32_bf16 v[58:61], v[200:203], v[162:165], v[58:61]
	v_mfma_f32_16x16x32_bf16 v[30:33], v[208:211], v[162:165], v[30:33]
	v_mfma_f32_16x16x32_bf16 v[10:13], v[216:219], v[162:165], v[10:13]
	s_add_u32 m0, m0, 0x400
	v_add_u32_e32 v226, 0x8000, v225
	global_load_lds_dwordx4 v226, s[22:23]
	v_mfma_f32_16x16x32_bf16 v[90:93], v[196:199], v[166:169], v[90:93]
	v_mfma_f32_16x16x32_bf16 v[58:61], v[204:207], v[166:169], v[58:61]
	v_mfma_f32_16x16x32_bf16 v[30:33], v[212:215], v[166:169], v[30:33]
	v_mfma_f32_16x16x32_bf16 v[10:13], v[220:223], v[166:169], v[10:13]
	s_add_u32 m0, m0, 0x400
	v_add_u32_e32 v226, 0xc000, v225
	global_load_lds_dwordx4 v226, s[22:23]
	ds_read_b128 v[162:165], v229 offset:14336
	ds_read_b128 v[166:169], v230 offset:14336
	s_waitcnt lgkmcnt(2)
	v_mfma_f32_16x16x32_bf16 v[82:85], v[192:195], v[154:157], v[82:85]
	v_mfma_f32_16x16x32_bf16 v[50:53], v[200:203], v[154:157], v[50:53]
	v_mfma_f32_16x16x32_bf16 v[22:25], v[208:211], v[154:157], v[22:25]
	v_mfma_f32_16x16x32_bf16 v[6:9], v[216:219], v[154:157], v[6:9]
	v_mfma_f32_16x16x32_bf16 v[82:85], v[196:199], v[158:161], v[82:85]
	v_mfma_f32_16x16x32_bf16 v[50:53], v[204:207], v[158:161], v[50:53]
	v_mfma_f32_16x16x32_bf16 v[22:25], v[212:215], v[158:161], v[22:25]
	v_mfma_f32_16x16x32_bf16 v[6:9], v[220:223], v[158:161], v[6:9]
	s_waitcnt lgkmcnt(0)
	v_mfma_f32_16x16x32_bf16 v[66:69], v[192:195], v[162:165], v[66:69]
	v_mfma_f32_16x16x32_bf16 v[34:37], v[200:203], v[162:165], v[34:37]
	v_mfma_f32_16x16x32_bf16 v[14:17], v[208:211], v[162:165], v[14:17]
	v_mfma_f32_16x16x32_bf16 v[2:5], v[216:219], v[162:165], v[2:5]
	v_mfma_f32_16x16x32_bf16 v[66:69], v[196:199], v[166:169], v[66:69]
	v_mfma_f32_16x16x32_bf16 v[34:37], v[204:207], v[166:169], v[34:37]
	v_mfma_f32_16x16x32_bf16 v[14:17], v[212:215], v[166:169], v[14:17]
	v_mfma_f32_16x16x32_bf16 v[2:5], v[220:223], v[166:169], v[2:5]
	v_xor_b32_e32 v229, 0x4000, v229
	v_xor_b32_e32 v230, 0x4000, v230
	s_add_i32 s21, s21, 1
	s_cmp_lg_u32 s21, 15
	s_cbranch_scc1 .Lbk64_418
	s_waitcnt vmcnt(0)
	s_barrier
	ds_read_b128 v[192:195], v227
	ds_read_b128 v[196:199], v228
	ds_read_b128 v[200:203], v227 offset:2048
	ds_read_b128 v[204:207], v228 offset:2048
	ds_read_b128 v[208:211], v227 offset:4096
	ds_read_b128 v[212:215], v228 offset:4096
	ds_read_b128 v[216:219], v227 offset:6144
	ds_read_b128 v[220:223], v228 offset:6144
	s_waitcnt lgkmcnt(0)
	ds_read_b128 v[154:157], v229 offset:0
	ds_read_b128 v[158:161], v230 offset:0
	ds_read_b128 v[162:165], v229 offset:2048
	ds_read_b128 v[166:169], v230 offset:2048
	s_waitcnt lgkmcnt(2)
	v_mfma_f32_16x16x32_bf16 v[126:129], v[192:195], v[154:157], v[126:129]
	v_mfma_f32_16x16x32_bf16 v[114:117], v[200:203], v[154:157], v[114:117]
	v_mfma_f32_16x16x32_bf16 v[94:97], v[208:211], v[154:157], v[94:97]
	v_mfma_f32_16x16x32_bf16 v[62:65], v[216:219], v[154:157], v[62:65]
	v_mfma_f32_16x16x32_bf16 v[126:129], v[196:199], v[158:161], v[126:129]
	v_mfma_f32_16x16x32_bf16 v[114:117], v[204:207], v[158:161], v[114:117]
	v_mfma_f32_16x16x32_bf16 v[94:97], v[212:215], v[158:161], v[94:97]
	v_mfma_f32_16x16x32_bf16 v[62:65], v[220:223], v[158:161], v[62:65]
	ds_read_b128 v[154:157], v229 offset:4096
	ds_read_b128 v[158:161], v230 offset:4096
	s_waitcnt lgkmcnt(2)
	v_mfma_f32_16x16x32_bf16 v[122:125], v[192:195], v[162:165], v[122:125]
	v_mfma_f32_16x16x32_bf16 v[106:109], v[200:203], v[162:165], v[106:109]
	v_mfma_f32_16x16x32_bf16 v[78:81], v[208:211], v[162:165], v[78:81]
	v_mfma_f32_16x16x32_bf16 v[46:49], v[216:219], v[162:165], v[46:49]
	v_mfma_f32_16x16x32_bf16 v[122:125], v[196:199], v[166:169], v[122:125]
	v_mfma_f32_16x16x32_bf16 v[106:109], v[204:207], v[166:169], v[106:109]
	v_mfma_f32_16x16x32_bf16 v[78:81], v[212:215], v[166:169], v[78:81]
	v_mfma_f32_16x16x32_bf16 v[46:49], v[220:223], v[166:169], v[46:49]
	ds_read_b128 v[162:165], v229 offset:6144
	ds_read_b128 v[166:169], v230 offset:6144
	s_waitcnt lgkmcnt(2)
	v_mfma_f32_16x16x32_bf16 v[118:121], v[192:195], v[154:157], v[118:121]
	v_mfma_f32_16x16x32_bf16 v[98:101], v[200:203], v[154:157], v[98:101]
	v_mfma_f32_16x16x32_bf16 v[70:73], v[208:211], v[154:157], v[70:73]
	v_mfma_f32_16x16x32_bf16 v[38:41], v[216:219], v[154:157], v[38:41]
	v_mfma_f32_16x16x32_bf16 v[118:121], v[196:199], v[158:161], v[118:121]
	v_mfma_f32_16x16x32_bf16 v[98:101], v[204:207], v[158:161], v[98:101]
	v_mfma_f32_16x16x32_bf16 v[70:73], v[212:215], v[158:161], v[70:73]
	v_mfma_f32_16x16x32_bf16 v[38:41], v[220:223], v[158:161], v[38:41]
	ds_read_b128 v[154:157], v229 offset:8192
	ds_read_b128 v[158:161], v230 offset:8192
	s_waitcnt lgkmcnt(2)
	v_mfma_f32_16x16x32_bf16 v[110:113], v[192:195], v[162:165], v[110:113]
	v_mfma_f32_16x16x32_bf16 v[86:89], v[200:203], v[162:165], v[86:89]
	v_mfma_f32_16x16x32_bf16 v[54:57], v[208:211], v[162:165], v[54:57]
	v_mfma_f32_16x16x32_bf16 v[26:29], v[216:219], v[162:165], v[26:29]
	v_mfma_f32_16x16x32_bf16 v[110:113], v[196:199], v[166:169], v[110:113]
	v_mfma_f32_16x16x32_bf16 v[86:89], v[204:207], v[166:169], v[86:89]
	v_mfma_f32_16x16x32_bf16 v[54:57], v[212:215], v[166:169], v[54:57]
	v_mfma_f32_16x16x32_bf16 v[26:29], v[220:223], v[166:169], v[26:29]
	ds_read_b128 v[162:165], v229 offset:10240
	ds_read_b128 v[166:169], v230 offset:10240
	s_waitcnt lgkmcnt(2)
	v_mfma_f32_16x16x32_bf16 v[102:105], v[192:195], v[154:157], v[102:105]
	v_mfma_f32_16x16x32_bf16 v[74:77], v[200:203], v[154:157], v[74:77]
	v_mfma_f32_16x16x32_bf16 v[42:45], v[208:211], v[154:157], v[42:45]
	v_mfma_f32_16x16x32_bf16 v[18:21], v[216:219], v[154:157], v[18:21]
	v_mfma_f32_16x16x32_bf16 v[102:105], v[196:199], v[158:161], v[102:105]
	v_mfma_f32_16x16x32_bf16 v[74:77], v[204:207], v[158:161], v[74:77]
	v_mfma_f32_16x16x32_bf16 v[42:45], v[212:215], v[158:161], v[42:45]
	v_mfma_f32_16x16x32_bf16 v[18:21], v[220:223], v[158:161], v[18:21]
	ds_read_b128 v[154:157], v229 offset:12288
	ds_read_b128 v[158:161], v230 offset:12288
	s_waitcnt lgkmcnt(2)
	v_mfma_f32_16x16x32_bf16 v[90:93], v[192:195], v[162:165], v[90:93]
	v_mfma_f32_16x16x32_bf16 v[58:61], v[200:203], v[162:165], v[58:61]
	v_mfma_f32_16x16x32_bf16 v[30:33], v[208:211], v[162:165], v[30:33]
	v_mfma_f32_16x16x32_bf16 v[10:13], v[216:219], v[162:165], v[10:13]
	v_mfma_f32_16x16x32_bf16 v[90:93], v[196:199], v[166:169], v[90:93]
	v_mfma_f32_16x16x32_bf16 v[58:61], v[204:207], v[166:169], v[58:61]
	v_mfma_f32_16x16x32_bf16 v[30:33], v[212:215], v[166:169], v[30:33]
	v_mfma_f32_16x16x32_bf16 v[10:13], v[220:223], v[166:169], v[10:13]
	ds_read_b128 v[162:165], v229 offset:14336
	ds_read_b128 v[166:169], v230 offset:14336
	s_waitcnt lgkmcnt(2)
	v_mfma_f32_16x16x32_bf16 v[82:85], v[192:195], v[154:157], v[82:85]
	v_mfma_f32_16x16x32_bf16 v[50:53], v[200:203], v[154:157], v[50:53]
	v_mfma_f32_16x16x32_bf16 v[22:25], v[208:211], v[154:157], v[22:25]
	v_mfma_f32_16x16x32_bf16 v[6:9], v[216:219], v[154:157], v[6:9]
	v_mfma_f32_16x16x32_bf16 v[82:85], v[196:199], v[158:161], v[82:85]
	v_mfma_f32_16x16x32_bf16 v[50:53], v[204:207], v[158:161], v[50:53]
	v_mfma_f32_16x16x32_bf16 v[22:25], v[212:215], v[158:161], v[22:25]
	v_mfma_f32_16x16x32_bf16 v[6:9], v[220:223], v[158:161], v[6:9]
	s_waitcnt lgkmcnt(0)
	v_mfma_f32_16x16x32_bf16 v[66:69], v[192:195], v[162:165], v[66:69]
	v_mfma_f32_16x16x32_bf16 v[34:37], v[200:203], v[162:165], v[34:37]
	v_mfma_f32_16x16x32_bf16 v[14:17], v[208:211], v[162:165], v[14:17]
	v_mfma_f32_16x16x32_bf16 v[2:5], v[216:219], v[162:165], v[2:5]
	v_mfma_f32_16x16x32_bf16 v[66:69], v[196:199], v[166:169], v[66:69]
	v_mfma_f32_16x16x32_bf16 v[34:37], v[204:207], v[166:169], v[34:37]
	v_mfma_f32_16x16x32_bf16 v[14:17], v[212:215], v[166:169], v[14:17]
	v_mfma_f32_16x16x32_bf16 v[2:5], v[220:223], v[166:169], v[2:5]
	s_nop 7
	s_nop 7
	s_waitcnt vmcnt(6)
	v_add_u32_e32 v142, v149, v147
	s_waitcnt lgkmcnt(0)
	v_and_b32_e32 v1, 0xfffffc0, v1
	v_lshl_or_b32 v1, v144, 2, v1
	v_mul_lo_u32 v1, v1, s33
	v_lshl_or_b32 v1, v143, 2, v1
	s_waitcnt lgkmcnt(0)
	s_waitcnt lgkmcnt(0)
	s_waitcnt lgkmcnt(0)
	s_waitcnt lgkmcnt(0)
	s_waitcnt lgkmcnt(0)
	v_mov_b64_e32 v[162:163], v[30:31]
	v_mov_b64_e32 v[164:165], v[32:33]
	v_mov_b64_e32 v[134:135], v[10:11]
	v_mov_b64_e32 v[136:137], v[12:13]
	s_nop 2
	s_waitcnt lgkmcnt(0)
	v_mov_b64_e32 v[180:181], v[6:7]
	v_mov_b64_e32 v[182:183], v[8:9]
	s_nop 2
	s_waitcnt vmcnt(0)
	v_mov_b64_e32 v[166:167], v[22:23]
	v_mov_b64_e32 v[168:169], v[24:25]
	s_waitcnt lgkmcnt(0)
	v_mov_b64_e32 v[130:131], v[34:35]
	v_mov_b64_e32 v[132:133], v[36:37]
	v_mov_b64_e32 v[138:139], v[14:15]
	v_mov_b64_e32 v[140:141], v[16:17]
	v_mov_b64_e32 v[158:159], v[2:3]
	v_mov_b64_e32 v[160:161], v[4:5]
	s_nop 1
	s_waitcnt lgkmcnt(0)
	v_mov_b64_e32 v[22:23], v[126:127]
	v_mov_b64_e32 v[24:25], v[128:129]
	s_nop 2
	v_mov_b64_e32 v[32:33], v[114:115]
	v_mov_b64_e32 v[34:35], v[116:117]
	s_nop 2
	s_waitcnt lgkmcnt(0)
	v_mov_b64_e32 v[2:3], v[122:123]
	v_mov_b64_e32 v[4:5], v[124:125]
	v_mov_b64_e32 v[122:123], v[46:47]
	v_mov_b64_e32 v[124:125], v[48:49]
	s_waitcnt lgkmcnt(0)
	v_mov_b64_e32 v[46:47], v[118:119]
	v_mov_b64_e32 v[48:49], v[120:121]
	v_mov_b64_e32 v[118:119], v[38:39]
	v_mov_b64_e32 v[120:121], v[40:41]
	v_mov_b64_e32 v[36:37], v[110:111]
	v_mov_b64_e32 v[38:39], v[112:113]
	s_nop 2
	s_waitcnt vmcnt(0) lgkmcnt(0)
	s_barrier
	ds_write2_b32 v1, v22, v2 offset1:16
	ds_write2_b32 v1, v23, v3 offset0:68 offset1:84
	ds_write2_b32 v1, v24, v4 offset0:136 offset1:152
	ds_write2_b32 v1, v25, v5 offset0:204 offset1:220
	ds_write2_b32 v1, v46, v36 offset0:32 offset1:48
	ds_write2_b32 v1, v47, v37 offset0:100 offset1:116
	ds_write2_b32 v1, v48, v38 offset0:168 offset1:184
	ds_write2_b32 v1, v49, v39 offset0:236 offset1:252
	v_mov_b64_e32 v[200:201], v[86:87]
	v_mov_b64_e32 v[202:203], v[88:89]
	s_nop 1
	v_add_u32_e32 v88, 0x1000, v1
	ds_write2_b32 v88, v32, v106 offset0:64 offset1:80
	ds_write2_b32 v88, v33, v107 offset0:132 offset1:148
	ds_write2_b32 v88, v34, v108 offset0:200 offset1:216
	v_add_u32_e32 v89, 0x1400, v1
	v_mov_b64_e32 v[212:213], v[26:27]
	v_mov_b64_e32 v[214:215], v[28:29]
	ds_write2_b32 v89, v35, v109 offset0:12 offset1:28
	ds_write2_b32 v88, v98, v200 offset0:96 offset1:112
	ds_write2_b32 v88, v99, v201 offset0:164 offset1:180
	ds_write2_b32 v88, v100, v202 offset0:232 offset1:248
	ds_write2_b32 v89, v101, v203 offset0:44 offset1:60
	v_mov_b64_e32 v[30:31], v[90:91]
	v_mov_b64_e32 v[32:33], v[92:93]
	s_nop 2
	v_add_u32_e32 v90, 0x2000, v1
	v_add_u32_e32 v91, 0x2400, v1
	ds_write2_b32 v90, v94, v78 offset0:128 offset1:144
	ds_write2_b32 v90, v95, v79 offset0:196 offset1:212
	ds_write2_b32 v91, v96, v80 offset0:8 offset1:24
	ds_write2_b32 v91, v97, v81 offset0:76 offset1:92
	ds_write2_b32 v90, v70, v54 offset0:160 offset1:176
	ds_write2_b32 v90, v71, v55 offset0:228 offset1:244
	ds_write2_b32 v91, v72, v56 offset0:40 offset1:56
	v_add_u32_e32 v92, 0x3000, v1
	v_add_u32_e32 v93, 0x3400, v1
	v_mov_b32_e32 v70, v170
	v_mov_b64_e32 v[6:7], v[42:43]
	v_mov_b64_e32 v[8:9], v[44:45]
	ds_write2_b32 v91, v73, v57 offset0:108 offset1:124
	ds_write2_b32 v92, v62, v122 offset0:192 offset1:208
	ds_write2_b32 v93, v63, v123 offset0:4 offset1:20
	ds_write2_b32 v93, v64, v124 offset0:72 offset1:88
	v_mov_b64_e32 v[42:43], v[50:51]
	v_mov_b64_e32 v[44:45], v[52:53]
	ds_write2_b32 v93, v65, v125 offset0:140 offset1:156
	ds_write2_b32 v92, v118, v212 offset0:224 offset1:240
	ds_write2_b32 v93, v119, v213 offset0:36 offset1:52
	ds_write2_b32 v93, v120, v214 offset0:104 offset1:120
	ds_write2_b32 v93, v121, v215 offset0:172 offset1:188
	s_waitcnt lgkmcnt(0)
	s_barrier
	v_mov_b64_e32 v[14:15], v[102:103]
	v_mov_b64_e32 v[16:17], v[104:105]
	v_ashrrev_i32_e32 v50, 7, v70
	v_mov_b64_e32 v[10:11], v[74:75]
	v_mov_b64_e32 v[12:13], v[76:77]
	v_mov_b64_e32 v[2:3], v[18:19]
	v_mov_b64_e32 v[4:5], v[20:21]
	v_mov_b64_e32 v[26:27], v[58:59]
	v_mov_b64_e32 v[28:29], v[60:61]
	v_mov_b64_e32 v[22:23], v[162:163]
	v_mov_b64_e32 v[24:25], v[164:165]
	v_mov_b64_e32 v[18:19], v[134:135]
	v_mov_b64_e32 v[20:21], v[136:137]
	v_mov_b64_e32 v[46:47], v[82:83]
	v_mov_b64_e32 v[48:49], v[84:85]
	v_mov_b64_e32 v[38:39], v[166:167]
	v_mov_b64_e32 v[40:41], v[168:169]
	v_mov_b64_e32 v[34:35], v[180:181]
	v_mov_b64_e32 v[36:37], v[182:183]
	v_mov_b64_e32 v[62:63], v[66:67]
	v_mov_b64_e32 v[64:65], v[68:69]
	v_mov_b64_e32 v[58:59], v[130:131]
	v_mov_b64_e32 v[60:61], v[132:133]
	s_nop 1
	v_add_u32_e32 v66, s46, v50
	v_cmp_lt_i32_e32 vcc, s91, v66
	v_mov_b64_e32 v[54:55], v[138:139]
	v_mov_b64_e32 v[56:57], v[140:141]
	v_mov_b64_e32 v[50:51], v[158:159]
	v_mov_b64_e32 v[52:53], v[160:161]
	s_and_saveexec_b64 s[4:5], vcc
	s_xor_b64 s[22:23], exec, s[4:5]
	v_add_u32_e32 v66, 0xfffffef0, v66
	v_mul_hi_u32 v67, v66, s96
	v_lshrrev_b32_e32 v67, 3, v67
	v_add_u32_e32 v68, 16, v67
	v_lshl_add_u32 v67, v67, 5, v67
	v_sub_u32_e32 v71, v66, v67
	s_or_saveexec_b64 s[22:23], s[22:23]
	v_mov_b32_e32 v72, 0x1000
	s_xor_b64 exec, exec, s[22:23]
	v_mul_hi_i32 v67, v66, s97
	v_lshrrev_b32_e32 v68, 31, v67
	v_ashrrev_i32_e32 v67, 3, v67
	v_add_u32_e32 v68, v67, v68
	v_lshl_add_u32 v67, v68, 4, v68
	v_sub_u32_e32 v71, v66, v67
	v_mov_b32_e32 v72, 0x800
	s_or_b64 exec, exec, s[22:23]
	v_cmp_lt_i32_e32 vcc, 15, v68
	s_and_saveexec_b64 s[4:5], vcc
	s_xor_b64 s[4:5], exec, s[4:5]
	v_add_u32_e32 v66, -16, v68
	v_mov_b32_e32 v67, v0
	v_lshlrev_b64 v[66:67], 12, v[66:67]
	v_lshl_add_u64 v[66:67], v[66:67], 0, s[42:43]
	s_andn2_saveexec_b64 s[22:23], s[4:5]
	v_ashrrev_i32_e32 v69, 31, v68
	v_lshlrev_b64 v[66:67], 11, v[68:69]
	s_or_b64 exec, exec, s[22:23]
	v_and_b32_e32 v69, 0x7f, v70
	v_cmp_gt_i32_e32 vcc, s79, v69
	s_and_saveexec_b64 s[22:23], vcc
	s_cbranch_execz .LBB0_436
	v_cmp_ne_u32_e32 vcc, 0, v69
	s_and_b64 exec, exec, vcc
	s_cbranch_execz .LBB0_436
	v_mul_lo_u32 v71, v71, s54
	v_add3_u32 v68, v69, v71, -1
	v_cmp_lt_i32_e32 vcc, v68, v72
	s_and_b64 exec, exec, vcc
	s_cbranch_execz .LBB0_436
	v_cmp_lt_i32_e32 vcc, 0, v68
	v_mov_b32_e32 v83, 0
	v_mov_b32_e32 v82, 0
	s_and_saveexec_b64 s[4:5], vcc
	v_mov_b32_e32 v73, 0x11ffc
	v_lshl_add_u32 v73, v70, 2, v73
	ds_read_b32 v82, v73
	s_or_b64 exec, exec, s[4:5]
	v_add_u32_e32 v69, v71, v69
	v_cmp_lt_i32_e32 vcc, v69, v72
	v_lshl_add_u32 v69, v70, 2, v175
	ds_read_b32 v84, v69
	s_and_saveexec_b64 s[4:5], vcc
	ds_read_b32 v83, v69 offset:4
	s_or_b64 exec, exec, s[4:5]
	s_lshl_b32 s4, s20, 6
	s_ashr_i32 s5, s4, 31
	s_lshl_b64 s[4:5], s[4:5], 1
	v_ashrrev_i32_e32 v69, 31, v68
	s_add_u32 s4, s38, s4
	v_lshl_add_u64 v[66:67], v[66:67], 0, v[68:69]
	v_mul_lo_u32 v68, v70, s33
	s_addc_u32 s5, s39, s5
	v_add_u32_e32 v94, 0xfffffef0, v68
	v_mov_b64_e32 v[68:69], s[4:5]
	v_mad_u64_u32 v[86:87], s[4:5], v66, s3, v[68:69]
	v_mov_b32_e32 v66, v87
	v_mad_u64_u32 v[66:67], s[4:5], v67, s3, v[66:67]
	v_mov_b32_e32 v87, v66
	s_mov_b32 s4, 0

.Lbk64_530:
	s_waitcnt vmcnt(0)
	s_barrier
	ds_read_b128 v[192:195], v227
	ds_read_b128 v[196:199], v228
	ds_read_b128 v[200:203], v227 offset:2048
	ds_read_b128 v[204:207], v228 offset:2048
	ds_read_b128 v[208:211], v227 offset:4096
	ds_read_b128 v[212:215], v228 offset:4096
	ds_read_b128 v[216:219], v227 offset:6144
	ds_read_b128 v[220:223], v228 offset:6144
	s_add_u32 s18, s18, 0x80
	s_addc_u32 s19, s19, 0
	s_waitcnt lgkmcnt(0)
	ds_read_b128 v[154:157], v229 offset:0
	ds_read_b128 v[158:161], v230 offset:0
	ds_read_b128 v[162:165], v229 offset:2048
	ds_read_b128 v[166:169], v230 offset:2048
	s_waitcnt lgkmcnt(2)
	v_mfma_f32_16x16x32_bf16 v[126:129], v[192:195], v[154:157], v[126:129]
	v_mfma_f32_16x16x32_bf16 v[114:117], v[200:203], v[154:157], v[114:117]
	v_mfma_f32_16x16x32_bf16 v[86:89], v[208:211], v[154:157], v[86:89]
	v_mfma_f32_16x16x32_bf16 v[54:57], v[216:219], v[154:157], v[54:57]
	v_readfirstlane_b32 s32, v145
	s_lshl_b32 m0, s32, 3
	v_mov_b32_e32 v226, v224
	global_load_lds_dwordx4 v226, s[18:19]
	v_mfma_f32_16x16x32_bf16 v[126:129], v[196:199], v[158:161], v[126:129]
	v_mfma_f32_16x16x32_bf16 v[114:117], v[204:207], v[158:161], v[114:117]
	v_mfma_f32_16x16x32_bf16 v[86:89], v[212:215], v[158:161], v[86:89]
	v_mfma_f32_16x16x32_bf16 v[54:57], v[220:223], v[158:161], v[54:57]
	s_add_u32 m0, m0, 0x400
	v_add_u32_e32 v226, 0x4000, v224
	global_load_lds_dwordx4 v226, s[18:19]
	ds_read_b128 v[154:157], v229 offset:4096
	ds_read_b128 v[158:161], v230 offset:4096
	s_waitcnt lgkmcnt(2)
	v_mfma_f32_16x16x32_bf16 v[122:125], v[192:195], v[162:165], v[122:125]
	v_mfma_f32_16x16x32_bf16 v[102:105], v[200:203], v[162:165], v[102:105]
	v_mfma_f32_16x16x32_bf16 v[70:73], v[208:211], v[162:165], v[70:73]
	v_mfma_f32_16x16x32_bf16 v[38:41], v[216:219], v[162:165], v[38:41]
	s_add_u32 m0, m0, 0x400
	v_add_u32_e32 v226, 0x8000, v224
	global_load_lds_dwordx4 v226, s[18:19]
	v_mfma_f32_16x16x32_bf16 v[122:125], v[196:199], v[166:169], v[122:125]
	v_mfma_f32_16x16x32_bf16 v[102:105], v[204:207], v[166:169], v[102:105]
	v_mfma_f32_16x16x32_bf16 v[70:73], v[212:215], v[166:169], v[70:73]
	v_mfma_f32_16x16x32_bf16 v[38:41], v[220:223], v[166:169], v[38:41]
	s_add_u32 m0, m0, 0x400
	v_add_u32_e32 v226, 0xc000, v224
	global_load_lds_dwordx4 v226, s[18:19]
	ds_read_b128 v[162:165], v229 offset:6144
	ds_read_b128 v[166:169], v230 offset:6144
	s_waitcnt lgkmcnt(2)
	v_mfma_f32_16x16x32_bf16 v[118:121], v[192:195], v[154:157], v[118:121]
	v_mfma_f32_16x16x32_bf16 v[90:93], v[200:203], v[154:157], v[90:93]
	v_mfma_f32_16x16x32_bf16 v[58:61], v[208:211], v[154:157], v[58:61]
	v_mfma_f32_16x16x32_bf16 v[26:29], v[216:219], v[154:157], v[26:29]
	s_add_u32 m0, m0, 0x400
	v_add_u32_e32 v226, 0x10000, v224
	global_load_lds_dwordx4 v226, s[18:19]
	v_mfma_f32_16x16x32_bf16 v[118:121], v[196:199], v[158:161], v[118:121]
	v_mfma_f32_16x16x32_bf16 v[90:93], v[204:207], v[158:161], v[90:93]
	v_mfma_f32_16x16x32_bf16 v[58:61], v[212:215], v[158:161], v[58:61]
	v_mfma_f32_16x16x32_bf16 v[26:29], v[220:223], v[158:161], v[26:29]
	s_add_u32 m0, m0, 0x400
	v_add_u32_e32 v226, 0x14000, v224
	global_load_lds_dwordx4 v226, s[18:19]
	ds_read_b128 v[154:157], v229 offset:8192
	ds_read_b128 v[158:161], v230 offset:8192
	s_waitcnt lgkmcnt(2)
	v_mfma_f32_16x16x32_bf16 v[110:113], v[192:195], v[162:165], v[110:113]
	v_mfma_f32_16x16x32_bf16 v[78:81], v[200:203], v[162:165], v[78:81]
	v_mfma_f32_16x16x32_bf16 v[46:49], v[208:211], v[162:165], v[46:49]
	v_mfma_f32_16x16x32_bf16 v[18:21], v[216:219], v[162:165], v[18:21]
	s_add_u32 m0, m0, 0x400
	v_add_u32_e32 v226, 0x18000, v224
	global_load_lds_dwordx4 v226, s[18:19]
	v_mfma_f32_16x16x32_bf16 v[110:113], v[196:199], v[166:169], v[110:113]
	v_mfma_f32_16x16x32_bf16 v[78:81], v[204:207], v[166:169], v[78:81]
	v_mfma_f32_16x16x32_bf16 v[46:49], v[212:215], v[166:169], v[46:49]
	v_mfma_f32_16x16x32_bf16 v[18:21], v[220:223], v[166:169], v[18:21]
	s_add_u32 m0, m0, 0x400
	v_add_u32_e32 v226, 0x1c000, v224
	global_load_lds_dwordx4 v226, s[18:19]
	ds_read_b128 v[162:165], v229 offset:10240
	ds_read_b128 v[166:169], v230 offset:10240
	s_waitcnt lgkmcnt(2)
	v_mfma_f32_16x16x32_bf16 v[106:109], v[192:195], v[154:157], v[106:109]
	v_mfma_f32_16x16x32_bf16 v[74:77], v[200:203], v[154:157], v[74:77]
	v_mfma_f32_16x16x32_bf16 v[42:45], v[208:211], v[154:157], v[42:45]
	v_mfma_f32_16x16x32_bf16 v[14:17], v[216:219], v[154:157], v[14:17]
	s_add_u32 m0, s25, 17
	s_and_b32 m0, m0, 1
	s_lshl_b32 m0, m0, 14
	s_add_u32 m0, m0, 0x8000
	v_readfirstlane_b32 s32, v145
	s_lshl_b32 s32, s32, 2
	s_add_u32 m0, m0, s32
	v_mov_b32_e32 v226, v225
	global_load_lds_dwordx4 v226, s[18:19]
	v_mfma_f32_16x16x32_bf16 v[106:109], v[196:199], v[158:161], v[106:109]
	v_mfma_f32_16x16x32_bf16 v[74:77], v[204:207], v[158:161], v[74:77]
	v_mfma_f32_16x16x32_bf16 v[42:45], v[212:215], v[158:161], v[42:45]
	v_mfma_f32_16x16x32_bf16 v[14:17], v[220:223], v[158:161], v[14:17]
	s_add_u32 m0, m0, 0x400
	v_add_u32_e32 v226, 0x4000, v225
	global_load_lds_dwordx4 v226, s[18:19]
	ds_read_b128 v[154:157], v229 offset:12288
	ds_read_b128 v[158:161], v230 offset:12288
	s_waitcnt lgkmcnt(2)
	v_mfma_f32_16x16x32_bf16 v[98:101], v[192:195], v[162:165], v[98:101]
	v_mfma_f32_16x16x32_bf16 v[66:69], v[200:203], v[162:165], v[66:69]
	v_mfma_f32_16x16x32_bf16 v[34:37], v[208:211], v[162:165], v[34:37]
	v_mfma_f32_16x16x32_bf16 v[10:13], v[216:219], v[162:165], v[10:13]
	s_add_u32 m0, m0, 0x400
	v_add_u32_e32 v226, 0x8000, v225
	global_load_lds_dwordx4 v226, s[18:19]
	v_mfma_f32_16x16x32_bf16 v[98:101], v[196:199], v[166:169], v[98:101]
	v_mfma_f32_16x16x32_bf16 v[66:69], v[204:207], v[166:169], v[66:69]
	v_mfma_f32_16x16x32_bf16 v[34:37], v[212:215], v[166:169], v[34:37]
	v_mfma_f32_16x16x32_bf16 v[10:13], v[220:223], v[166:169], v[10:13]
	s_add_u32 m0, m0, 0x400
	v_add_u32_e32 v226, 0xc000, v225
	global_load_lds_dwordx4 v226, s[18:19]
	ds_read_b128 v[162:165], v229 offset:14336
	ds_read_b128 v[166:169], v230 offset:14336
	s_waitcnt lgkmcnt(2)
	v_mfma_f32_16x16x32_bf16 v[94:97], v[192:195], v[154:157], v[94:97]
	v_mfma_f32_16x16x32_bf16 v[62:65], v[200:203], v[154:157], v[62:65]
	v_mfma_f32_16x16x32_bf16 v[30:33], v[208:211], v[154:157], v[30:33]
	v_mfma_f32_16x16x32_bf16 v[6:9], v[216:219], v[154:157], v[6:9]
	v_mfma_f32_16x16x32_bf16 v[94:97], v[196:199], v[158:161], v[94:97]
	v_mfma_f32_16x16x32_bf16 v[62:65], v[204:207], v[158:161], v[62:65]
	v_mfma_f32_16x16x32_bf16 v[30:33], v[212:215], v[158:161], v[30:33]
	v_mfma_f32_16x16x32_bf16 v[6:9], v[220:223], v[158:161], v[6:9]
	s_waitcnt lgkmcnt(0)
	v_mfma_f32_16x16x32_bf16 v[82:85], v[192:195], v[162:165], v[82:85]
	v_mfma_f32_16x16x32_bf16 v[50:53], v[200:203], v[162:165], v[50:53]
	v_mfma_f32_16x16x32_bf16 v[22:25], v[208:211], v[162:165], v[22:25]
	v_mfma_f32_16x16x32_bf16 v[2:5], v[216:219], v[162:165], v[2:5]
	v_mfma_f32_16x16x32_bf16 v[82:85], v[196:199], v[166:169], v[82:85]
	v_mfma_f32_16x16x32_bf16 v[50:53], v[204:207], v[166:169], v[50:53]
	v_mfma_f32_16x16x32_bf16 v[22:25], v[212:215], v[166:169], v[22:25]
	v_mfma_f32_16x16x32_bf16 v[2:5], v[220:223], v[166:169], v[2:5]
	v_xor_b32_e32 v229, 0x4000, v229
	v_xor_b32_e32 v230, 0x4000, v230
	s_add_i32 s25, s25, 1
	s_cmp_lg_u32 s25, 15
	s_cbranch_scc1 .Lbk64_530
	s_waitcnt vmcnt(0)
	s_barrier
	ds_read_b128 v[192:195], v227
	ds_read_b128 v[196:199], v228
	ds_read_b128 v[200:203], v227 offset:2048
	ds_read_b128 v[204:207], v228 offset:2048
	ds_read_b128 v[208:211], v227 offset:4096
	ds_read_b128 v[212:215], v228 offset:4096
	ds_read_b128 v[216:219], v227 offset:6144
	ds_read_b128 v[220:223], v228 offset:6144
	s_waitcnt lgkmcnt(0)
	ds_read_b128 v[154:157], v229 offset:0
	ds_read_b128 v[158:161], v230 offset:0
	ds_read_b128 v[162:165], v229 offset:2048
	ds_read_b128 v[166:169], v230 offset:2048
	s_waitcnt lgkmcnt(2)
	v_mfma_f32_16x16x32_bf16 v[126:129], v[192:195], v[154:157], v[126:129]
	v_mfma_f32_16x16x32_bf16 v[114:117], v[200:203], v[154:157], v[114:117]
	v_mfma_f32_16x16x32_bf16 v[86:89], v[208:211], v[154:157], v[86:89]
	v_mfma_f32_16x16x32_bf16 v[54:57], v[216:219], v[154:157], v[54:57]
	v_mfma_f32_16x16x32_bf16 v[126:129], v[196:199], v[158:161], v[126:129]
	v_mfma_f32_16x16x32_bf16 v[114:117], v[204:207], v[158:161], v[114:117]
	v_mfma_f32_16x16x32_bf16 v[86:89], v[212:215], v[158:161], v[86:89]
	v_mfma_f32_16x16x32_bf16 v[54:57], v[220:223], v[158:161], v[54:57]
	ds_read_b128 v[154:157], v229 offset:4096
	ds_read_b128 v[158:161], v230 offset:4096
	s_waitcnt lgkmcnt(2)
	v_mfma_f32_16x16x32_bf16 v[122:125], v[192:195], v[162:165], v[122:125]
	v_mfma_f32_16x16x32_bf16 v[102:105], v[200:203], v[162:165], v[102:105]
	v_mfma_f32_16x16x32_bf16 v[70:73], v[208:211], v[162:165], v[70:73]
	v_mfma_f32_16x16x32_bf16 v[38:41], v[216:219], v[162:165], v[38:41]
	v_mfma_f32_16x16x32_bf16 v[122:125], v[196:199], v[166:169], v[122:125]
	v_mfma_f32_16x16x32_bf16 v[102:105], v[204:207], v[166:169], v[102:105]
	v_mfma_f32_16x16x32_bf16 v[70:73], v[212:215], v[166:169], v[70:73]
	v_mfma_f32_16x16x32_bf16 v[38:41], v[220:223], v[166:169], v[38:41]
	ds_read_b128 v[162:165], v229 offset:6144
	ds_read_b128 v[166:169], v230 offset:6144
	s_waitcnt lgkmcnt(2)
	v_mfma_f32_16x16x32_bf16 v[118:121], v[192:195], v[154:157], v[118:121]
	v_mfma_f32_16x16x32_bf16 v[90:93], v[200:203], v[154:157], v[90:93]
	v_mfma_f32_16x16x32_bf16 v[58:61], v[208:211], v[154:157], v[58:61]
	v_mfma_f32_16x16x32_bf16 v[26:29], v[216:219], v[154:157], v[26:29]
	v_mfma_f32_16x16x32_bf16 v[118:121], v[196:199], v[158:161], v[118:121]
	v_mfma_f32_16x16x32_bf16 v[90:93], v[204:207], v[158:161], v[90:93]
	v_mfma_f32_16x16x32_bf16 v[58:61], v[212:215], v[158:161], v[58:61]
	v_mfma_f32_16x16x32_bf16 v[26:29], v[220:223], v[158:161], v[26:29]
	ds_read_b128 v[154:157], v229 offset:8192
	ds_read_b128 v[158:161], v230 offset:8192
	s_waitcnt lgkmcnt(2)
	v_mfma_f32_16x16x32_bf16 v[110:113], v[192:195], v[162:165], v[110:113]
	v_mfma_f32_16x16x32_bf16 v[78:81], v[200:203], v[162:165], v[78:81]
	v_mfma_f32_16x16x32_bf16 v[46:49], v[208:211], v[162:165], v[46:49]
	v_mfma_f32_16x16x32_bf16 v[18:21], v[216:219], v[162:165], v[18:21]
	v_mfma_f32_16x16x32_bf16 v[110:113], v[196:199], v[166:169], v[110:113]
	v_mfma_f32_16x16x32_bf16 v[78:81], v[204:207], v[166:169], v[78:81]
	v_mfma_f32_16x16x32_bf16 v[46:49], v[212:215], v[166:169], v[46:49]
	v_mfma_f32_16x16x32_bf16 v[18:21], v[220:223], v[166:169], v[18:21]
	ds_read_b128 v[162:165], v229 offset:10240
	ds_read_b128 v[166:169], v230 offset:10240
	s_waitcnt lgkmcnt(2)
	v_mfma_f32_16x16x32_bf16 v[106:109], v[192:195], v[154:157], v[106:109]
	v_mfma_f32_16x16x32_bf16 v[74:77], v[200:203], v[154:157], v[74:77]
	v_mfma_f32_16x16x32_bf16 v[42:45], v[208:211], v[154:157], v[42:45]
	v_mfma_f32_16x16x32_bf16 v[14:17], v[216:219], v[154:157], v[14:17]
	v_mfma_f32_16x16x32_bf16 v[106:109], v[196:199], v[158:161], v[106:109]
	v_mfma_f32_16x16x32_bf16 v[74:77], v[204:207], v[158:161], v[74:77]
	v_mfma_f32_16x16x32_bf16 v[42:45], v[212:215], v[158:161], v[42:45]
	v_mfma_f32_16x16x32_bf16 v[14:17], v[220:223], v[158:161], v[14:17]
	ds_read_b128 v[154:157], v229 offset:12288
	ds_read_b128 v[158:161], v230 offset:12288
	s_waitcnt lgkmcnt(2)
	v_mfma_f32_16x16x32_bf16 v[98:101], v[192:195], v[162:165], v[98:101]
	v_mfma_f32_16x16x32_bf16 v[66:69], v[200:203], v[162:165], v[66:69]
	v_mfma_f32_16x16x32_bf16 v[34:37], v[208:211], v[162:165], v[34:37]
	v_mfma_f32_16x16x32_bf16 v[10:13], v[216:219], v[162:165], v[10:13]
	v_mfma_f32_16x16x32_bf16 v[98:101], v[196:199], v[166:169], v[98:101]
	v_mfma_f32_16x16x32_bf16 v[66:69], v[204:207], v[166:169], v[66:69]
	v_mfma_f32_16x16x32_bf16 v[34:37], v[212:215], v[166:169], v[34:37]
	v_mfma_f32_16x16x32_bf16 v[10:13], v[220:223], v[166:169], v[10:13]
	ds_read_b128 v[162:165], v229 offset:14336
	ds_read_b128 v[166:169], v230 offset:14336
	s_waitcnt lgkmcnt(2)
	v_mfma_f32_16x16x32_bf16 v[94:97], v[192:195], v[154:157], v[94:97]
	v_mfma_f32_16x16x32_bf16 v[62:65], v[200:203], v[154:157], v[62:65]
	v_mfma_f32_16x16x32_bf16 v[30:33], v[208:211], v[154:157], v[30:33]
	v_mfma_f32_16x16x32_bf16 v[6:9], v[216:219], v[154:157], v[6:9]
	v_mfma_f32_16x16x32_bf16 v[94:97], v[196:199], v[158:161], v[94:97]
	v_mfma_f32_16x16x32_bf16 v[62:65], v[204:207], v[158:161], v[62:65]
	v_mfma_f32_16x16x32_bf16 v[30:33], v[212:215], v[158:161], v[30:33]
	v_mfma_f32_16x16x32_bf16 v[6:9], v[220:223], v[158:161], v[6:9]
	s_waitcnt lgkmcnt(0)
	v_mfma_f32_16x16x32_bf16 v[82:85], v[192:195], v[162:165], v[82:85]
	v_mfma_f32_16x16x32_bf16 v[50:53], v[200:203], v[162:165], v[50:53]
	v_mfma_f32_16x16x32_bf16 v[22:25], v[208:211], v[162:165], v[22:25]
	v_mfma_f32_16x16x32_bf16 v[2:5], v[216:219], v[162:165], v[2:5]
	v_mfma_f32_16x16x32_bf16 v[82:85], v[196:199], v[166:169], v[82:85]
	v_mfma_f32_16x16x32_bf16 v[50:53], v[204:207], v[166:169], v[50:53]
	v_mfma_f32_16x16x32_bf16 v[22:25], v[212:215], v[166:169], v[22:25]
	v_mfma_f32_16x16x32_bf16 v[2:5], v[220:223], v[166:169], v[2:5]
	s_nop 7
	s_nop 7
	s_waitcnt vmcnt(6)
	v_add_u32_e32 v145, v149, v147
	s_waitcnt vmcnt(0)
	s_waitcnt lgkmcnt(0)
	s_lshl_b32 s18, s16, 7
	s_ashr_i32 s19, s18, 31
	s_lshl_b64 s[18:19], s[18:19], 1
	v_and_b32_e32 v1, 0xfffffc0, v1
	v_lshl_or_b32 v1, v143, 2, v1
	v_mul_lo_u32 v1, v1, s33
	v_lshl_or_b32 v1, v142, 2, v1
	s_lshl_b32 s16, s16, 1
	s_ashr_i32 s17, s16, 31
	s_lshl_b64 s[16:17], s[16:17], 2
	s_add_i32 s24, s24, 1
	v_mov_b64_e32 v[162:163], v[62:63]
	v_mov_b64_e32 v[164:165], v[64:65]
	v_mov_b64_e32 v[166:167], v[30:31]
	v_mov_b64_e32 v[168:169], v[32:33]
	v_mov_b64_e32 v[130:131], v[22:23]
	v_mov_b64_e32 v[132:133], v[24:25]
	s_waitcnt lgkmcnt(0)
	v_mov_b64_e32 v[232:233], v[38:39]
	v_mov_b64_e32 v[234:235], v[40:41]
	v_mov_b64_e32 v[38:39], v[34:35]
	v_mov_b64_e32 v[40:41], v[36:37]
	v_mov_b64_e32 v[34:35], v[2:3]
	v_mov_b64_e32 v[36:37], v[4:5]
	s_nop 2
	v_mov_b32_e32 v2, v170
	v_mov_b64_e32 v[216:217], v[114:115]
	v_mov_b64_e32 v[218:219], v[116:117]
	v_add_u32_e32 v2, s4, v2
	v_ashrrev_i32_e32 v3, 31, v2
	v_lshlrev_b64 v[2:3], 11, v[2:3]
	v_lshl_add_u64 v[2:3], s[8:9], 0, v[2:3]
	v_lshl_add_u64 v[2:3], v[2:3], 0, s[18:19]
	v_mov_b64_e32 v[220:221], v[54:55]
	v_mov_b64_e32 v[222:223], v[56:57]
	v_mov_b64_e32 v[224:225], v[122:123]
	v_mov_b64_e32 v[226:227], v[124:125]
	v_mov_b64_e32 v[228:229], v[102:103]
	v_mov_b64_e32 v[230:231], v[104:105]
	v_mov_b64_e32 v[236:237], v[118:119]
	v_mov_b64_e32 v[238:239], v[120:121]
	v_mov_b64_e32 v[240:241], v[58:59]
	v_mov_b64_e32 v[242:243], v[60:61]
	v_mov_b64_e32 v[244:245], v[26:27]
	v_mov_b64_e32 v[246:247], v[28:29]
	v_mov_b64_e32 v[248:249], v[110:111]
	v_mov_b64_e32 v[250:251], v[112:113]
	v_mov_b64_e32 v[180:181], v[78:79]
	v_mov_b64_e32 v[182:183], v[80:81]
	v_mov_b64_e32 v[154:155], v[46:47]
	v_mov_b64_e32 v[156:157], v[48:49]
	v_mov_b64_e32 v[62:63], v[106:107]
	v_mov_b64_e32 v[64:65], v[108:109]
	v_mov_b64_e32 v[46:47], v[74:75]
	v_mov_b64_e32 v[48:49], v[76:77]
	v_mov_b64_e32 v[74:75], v[98:99]
	v_mov_b64_e32 v[76:77], v[100:101]
	v_mov_b64_e32 v[54:55], v[66:67]
	v_mov_b64_e32 v[56:57], v[68:69]
	v_mov_b64_e32 v[58:59], v[162:163]
	v_mov_b64_e32 v[60:61], v[164:165]
	v_mov_b64_e32 v[66:67], v[50:51]
	v_mov_b64_e32 v[68:69], v[52:53]
	flat_load_dwordx4 v[138:141], v[2:3]
	flat_load_dwordx4 v[122:125], v[2:3] offset:16
	flat_load_dwordx4 v[118:121], v[2:3] offset:32
	flat_load_dwordx4 v[114:117], v[2:3] offset:48
	flat_load_dwordx4 v[110:113], v[2:3] offset:64
	flat_load_dwordx4 v[106:109], v[2:3] offset:80
	flat_load_dwordx4 v[102:105], v[2:3] offset:96
	flat_load_dwordx4 v[98:101], v[2:3] offset:112
	s_waitcnt vmcnt(0) lgkmcnt(0)
	s_barrier
	s_nop 7
	ds_write2_b32 v1, v126, v224 offset1:16
	ds_write2_b32 v1, v127, v225 offset0:68 offset1:84
	ds_write2_b32 v1, v128, v226 offset0:136 offset1:152
	ds_write2_b32 v1, v129, v227 offset0:204 offset1:220
	ds_write2_b32 v1, v236, v248 offset0:32 offset1:48
	ds_write2_b32 v1, v237, v249 offset0:100 offset1:116
	ds_write2_b32 v1, v238, v250 offset0:168 offset1:184
	ds_write2_b32 v1, v239, v251 offset0:236 offset1:252
	v_mov_b64_e32 v[196:197], v[18:19]
	v_mov_b64_e32 v[198:199], v[20:21]
	v_mov_b64_e32 v[78:79], v[94:95]
	v_mov_b64_e32 v[80:81], v[96:97]
	v_add_u32_e32 v135, 0x3000, v1
	v_add_u32_e32 v134, 0x3400, v1
	v_mov_b32_e32 v136, v170
	v_mov_b64_e32 v[50:51], v[130:131]
	v_mov_b64_e32 v[52:53], v[132:133]
	v_lshlrev_b32_e32 v137, 16, v138
	s_nop 1
	v_add_u32_e32 v130, 0x1000, v1
	v_add_u32_e32 v131, 0x1400, v1
	v_add_u32_e32 v132, 0x2000, v1
	v_add_u32_e32 v133, 0x2400, v1
	ds_write2_b32 v130, v216, v228 offset0:64 offset1:80
	ds_write2_b32 v130, v217, v229 offset0:132 offset1:148
	ds_write2_b32 v130, v218, v230 offset0:200 offset1:216
	ds_write2_b32 v131, v219, v231 offset0:12 offset1:28
	ds_write2_b32 v130, v90, v180 offset0:96 offset1:112
	ds_write2_b32 v130, v91, v181 offset0:164 offset1:180
	ds_write2_b32 v130, v92, v182 offset0:232 offset1:248
	ds_write2_b32 v131, v93, v183 offset0:44 offset1:60
	ds_write2_b32 v132, v86, v70 offset0:128 offset1:144
	ds_write2_b32 v132, v87, v71 offset0:196 offset1:212
	ds_write2_b32 v133, v88, v72 offset0:8 offset1:24
	ds_write2_b32 v133, v89, v73 offset0:76 offset1:92
	ds_write2_b32 v132, v240, v154 offset0:160 offset1:176
	ds_write2_b32 v132, v241, v155 offset0:228 offset1:244
	ds_write2_b32 v133, v242, v156 offset0:40 offset1:56
	ds_write2_b32 v133, v243, v157 offset0:108 offset1:124
	ds_write2_b32 v135, v220, v232 offset0:192 offset1:208
	ds_write2_b32 v134, v221, v233 offset0:4 offset1:20
	ds_write2_b32 v134, v222, v234 offset0:72 offset1:88
	ds_write2_b32 v134, v223, v235 offset0:140 offset1:156
	ds_write2_b32 v135, v244, v196 offset0:224 offset1:240
	ds_write2_b32 v134, v245, v197 offset0:36 offset1:52
	ds_write2_b32 v134, v246, v198 offset0:104 offset1:120
	ds_write2_b32 v134, v247, v199 offset0:172 offset1:188
	s_waitcnt lgkmcnt(0)
	s_barrier
	v_mov_b64_e32 v[18:19], v[14:15]
	v_mov_b64_e32 v[20:21], v[16:17]
	v_add_u32_e32 v126, s4, v136
	v_ashrrev_i32_e32 v127, 31, v126
	v_lshlrev_b64 v[2:3], 11, v[126:127]
	v_lshl_add_u64 v[2:3], s[8:9], 0, v[2:3]
	v_lshl_add_u64 v[128:129], v[2:3], 0, s[18:19]
	v_mul_lo_u32 v136, v136, s33
	v_mov_b64_e32 v[22:23], v[10:11]
	v_mov_b64_e32 v[24:25], v[12:13]
	v_and_b32_e32 v138, 0xffff0000, v138
	v_mov_b64_e32 v[26:27], v[6:7]
	v_mov_b64_e32 v[28:29], v[8:9]
	flat_load_dwordx4 v[94:97], v[128:129] offset:128
	flat_load_dwordx4 v[90:93], v[128:129] offset:144
	flat_load_dwordx4 v[86:89], v[128:129] offset:160
	flat_load_dwordx4 v[70:73], v[128:129] offset:176
	flat_load_dwordx4 v[14:17], v[128:129] offset:192
	flat_load_dwordx4 v[10:13], v[128:129] offset:208
	flat_load_dwordx4 v[6:9], v[128:129] offset:224
	flat_load_dwordx4 v[2:5], v[128:129] offset:240
	ds_read_b128 v[142:145], v136
	ds_read_b128 v[154:157], v136 offset:16
	s_waitcnt lgkmcnt(0)
	v_add_f32_e32 v137, v142, v137
	v_add_f32_e32 v138, v143, v138
	v_cvt_pk_bf16_f32 v138, v137, v138
	v_lshlrev_b32_e32 v137, 16, v139
	v_and_b32_e32 v139, 0xffff0000, v139
	v_add_f32_e32 v137, v144, v137
	v_add_f32_e32 v139, v145, v139
	v_cvt_pk_bf16_f32 v139, v137, v139
	v_lshlrev_b32_e32 v137, 16, v140
	v_and_b32_e32 v140, 0xffff0000, v140
	v_add_f32_e32 v137, v154, v137
	v_add_f32_e32 v140, v155, v140
	v_cvt_pk_bf16_f32 v140, v137, v140
	v_lshlrev_b32_e32 v137, 16, v141
	v_and_b32_e32 v141, 0xffff0000, v141
	v_add_f32_e32 v137, v156, v137
	v_add_f32_e32 v141, v157, v141
	v_and_b32_e32 v142, 0xffff0000, v138
	v_cvt_pk_bf16_f32 v141, v137, v141
	v_lshlrev_b32_e32 v137, 16, v138
	v_mul_f32_e32 v153, v142, v142
	v_lshlrev_b32_e32 v143, 16, v139
	v_fmac_f32_e32 v153, v137, v137
	v_and_b32_e32 v144, 0xffff0000, v139
	v_fmac_f32_e32 v153, v143, v143
	v_lshlrev_b32_e32 v145, 16, v140
	v_fmac_f32_e32 v153, v144, v144
	flat_store_dwordx4 v[128:129], v[138:141]
	v_and_b32_e32 v147, 0xffff0000, v140
	v_lshlrev_b32_e32 v149, 16, v141
	v_and_b32_e32 v151, 0xffff0000, v141
	v_fmac_f32_e32 v153, v145, v145
	ds_read_b128 v[138:141], v136 offset:32
	ds_read_b128 v[142:145], v136 offset:48
	v_lshlrev_b32_e32 v137, 16, v122
	v_and_b32_e32 v122, 0xffff0000, v122
	v_fmac_f32_e32 v153, v147, v147
	s_waitcnt lgkmcnt(0)
	v_add_f32_e32 v137, v138, v137
	v_add_f32_e32 v122, v139, v122
	v_cvt_pk_bf16_f32 v122, v137, v122
	v_lshlrev_b32_e32 v137, 16, v123
	v_and_b32_e32 v123, 0xffff0000, v123
	v_add_f32_e32 v137, v140, v137
	v_add_f32_e32 v123, v141, v123
	v_cvt_pk_bf16_f32 v123, v137, v123
	v_lshlrev_b32_e32 v137, 16, v124
	v_and_b32_e32 v124, 0xffff0000, v124
	v_add_f32_e32 v137, v142, v137
	v_add_f32_e32 v124, v143, v124
	v_cvt_pk_bf16_f32 v124, v137, v124
	v_lshlrev_b32_e32 v137, 16, v125
	v_and_b32_e32 v125, 0xffff0000, v125
	v_add_f32_e32 v137, v144, v137
	v_add_f32_e32 v125, v145, v125
	v_and_b32_e32 v138, 0xffff0000, v122
	v_cvt_pk_bf16_f32 v125, v137, v125
	v_lshlrev_b32_e32 v137, 16, v122
	v_mul_f32_e32 v138, v138, v138
	v_lshlrev_b32_e32 v139, 16, v123
	v_fmac_f32_e32 v138, v137, v137
	v_and_b32_e32 v140, 0xffff0000, v123
	v_fmac_f32_e32 v138, v139, v139
	v_lshlrev_b32_e32 v141, 16, v124
	v_fmac_f32_e32 v138, v140, v140
	v_and_b32_e32 v142, 0xffff0000, v124
	v_fmac_f32_e32 v138, v141, v141
	v_lshlrev_b32_e32 v143, 16, v125
	v_fmac_f32_e32 v138, v142, v142
	v_fmac_f32_e32 v153, v149, v149
	v_and_b32_e32 v144, 0xffff0000, v125
	v_fmac_f32_e32 v138, v143, v143
	v_fmac_f32_e32 v153, v151, v151
	v_fmac_f32_e32 v138, v144, v144
	flat_store_dwordx4 v[128:129], v[122:125] offset:16
	v_add_f32_e32 v137, v153, v138
	ds_read_b128 v[122:125], v136 offset:64
	ds_read_b128 v[138:141], v136 offset:80
	v_lshlrev_b32_e32 v142, 16, v118
	v_and_b32_e32 v118, 0xffff0000, v118
	v_mov_b64_e32 v[30:31], v[42:43]
	v_mov_b64_e32 v[32:33], v[44:45]
	s_waitcnt lgkmcnt(0)
	v_add_f32_e32 v122, v122, v142
	v_add_f32_e32 v118, v123, v118
	v_cvt_pk_bf16_f32 v118, v122, v118
	v_lshlrev_b32_e32 v122, 16, v119
	v_and_b32_e32 v119, 0xffff0000, v119
	v_add_f32_e32 v122, v124, v122
	v_add_f32_e32 v119, v125, v119
	v_cvt_pk_bf16_f32 v119, v122, v119
	v_lshlrev_b32_e32 v122, 16, v120
	v_and_b32_e32 v120, 0xffff0000, v120
	v_add_f32_e32 v122, v138, v122
	v_add_f32_e32 v120, v139, v120
	v_cvt_pk_bf16_f32 v120, v122, v120
	v_lshlrev_b32_e32 v122, 16, v121
	v_and_b32_e32 v121, 0xffff0000, v121
	v_add_f32_e32 v122, v140, v122
	v_add_f32_e32 v121, v141, v121
	v_and_b32_e32 v123, 0xffff0000, v118
	v_cvt_pk_bf16_f32 v121, v122, v121
	v_lshlrev_b32_e32 v122, 16, v118
	v_mul_f32_e32 v123, v123, v123
	v_lshlrev_b32_e32 v124, 16, v119
	v_fmac_f32_e32 v123, v122, v122
	v_and_b32_e32 v125, 0xffff0000, v119
	v_fmac_f32_e32 v123, v124, v124
	v_lshlrev_b32_e32 v138, 16, v120
	v_fmac_f32_e32 v123, v125, v125
	v_and_b32_e32 v139, 0xffff0000, v120
	v_fmac_f32_e32 v123, v138, v138
	v_lshlrev_b32_e32 v140, 16, v121
	v_fmac_f32_e32 v123, v139, v139
	v_and_b32_e32 v141, 0xffff0000, v121
	v_fmac_f32_e32 v123, v140, v140
	v_fmac_f32_e32 v123, v141, v141
	flat_store_dwordx4 v[128:129], v[118:121] offset:32
	v_add_f32_e32 v137, v137, v123
	ds_read_b128 v[118:121], v136 offset:96
	ds_read_b128 v[122:125], v136 offset:112
	v_lshlrev_b32_e32 v138, 16, v114
	v_and_b32_e32 v114, 0xffff0000, v114
	v_mov_b64_e32 v[42:43], v[166:167]
	v_mov_b64_e32 v[44:45], v[168:169]
	s_waitcnt lgkmcnt(0)
	v_add_f32_e32 v118, v118, v138
	v_add_f32_e32 v114, v119, v114
	v_cvt_pk_bf16_f32 v114, v118, v114
	v_lshlrev_b32_e32 v118, 16, v115
	v_and_b32_e32 v115, 0xffff0000, v115
	v_add_f32_e32 v118, v120, v118
	v_add_f32_e32 v115, v121, v115
	v_cvt_pk_bf16_f32 v115, v118, v115
	v_lshlrev_b32_e32 v118, 16, v116
	v_and_b32_e32 v116, 0xffff0000, v116
	v_add_f32_e32 v118, v122, v118
	v_add_f32_e32 v116, v123, v116
	v_cvt_pk_bf16_f32 v116, v118, v116
	v_lshlrev_b32_e32 v118, 16, v117
	v_and_b32_e32 v117, 0xffff0000, v117
	v_add_f32_e32 v118, v124, v118
	v_add_f32_e32 v117, v125, v117
	v_and_b32_e32 v119, 0xffff0000, v114
	v_cvt_pk_bf16_f32 v117, v118, v117
	v_lshlrev_b32_e32 v118, 16, v114
	v_mul_f32_e32 v119, v119, v119
	v_lshlrev_b32_e32 v120, 16, v115
	v_fmac_f32_e32 v119, v118, v118
	v_and_b32_e32 v121, 0xffff0000, v115
	v_fmac_f32_e32 v119, v120, v120
	v_lshlrev_b32_e32 v122, 16, v116
	v_fmac_f32_e32 v119, v121, v121
	v_and_b32_e32 v123, 0xffff0000, v116
	v_fmac_f32_e32 v119, v122, v122
	v_lshlrev_b32_e32 v124, 16, v117
	v_fmac_f32_e32 v119, v123, v123
	v_and_b32_e32 v125, 0xffff0000, v117
	v_fmac_f32_e32 v119, v124, v124
	v_fmac_f32_e32 v119, v125, v125
	flat_store_dwordx4 v[128:129], v[114:117] offset:48
	v_add_f32_e32 v122, v137, v119
	ds_read_b128 v[114:117], v136 offset:128
	ds_read_b128 v[118:121], v136 offset:144
	v_lshlrev_b32_e32 v123, 16, v110
	v_and_b32_e32 v110, 0xffff0000, v110
	s_waitcnt lgkmcnt(0)
	v_add_f32_e32 v114, v114, v123
	v_add_f32_e32 v110, v115, v110
	v_cvt_pk_bf16_f32 v110, v114, v110
	v_lshlrev_b32_e32 v114, 16, v111
	v_and_b32_e32 v111, 0xffff0000, v111
	v_add_f32_e32 v114, v116, v114
	v_add_f32_e32 v111, v117, v111
	v_cvt_pk_bf16_f32 v111, v114, v111
	v_lshlrev_b32_e32 v114, 16, v112
	v_and_b32_e32 v112, 0xffff0000, v112
	v_add_f32_e32 v114, v118, v114
	v_add_f32_e32 v112, v119, v112
	v_cvt_pk_bf16_f32 v112, v114, v112
	v_lshlrev_b32_e32 v114, 16, v113
	v_and_b32_e32 v113, 0xffff0000, v113
	v_add_f32_e32 v114, v120, v114
	v_add_f32_e32 v113, v121, v113
	v_and_b32_e32 v115, 0xffff0000, v110
	v_cvt_pk_bf16_f32 v113, v114, v113
	v_lshlrev_b32_e32 v114, 16, v110
	v_mul_f32_e32 v115, v115, v115
	v_lshlrev_b32_e32 v116, 16, v111
	v_fmac_f32_e32 v115, v114, v114
	v_and_b32_e32 v117, 0xffff0000, v111
	v_fmac_f32_e32 v115, v116, v116
	v_lshlrev_b32_e32 v118, 16, v112
	v_fmac_f32_e32 v115, v117, v117
	v_and_b32_e32 v119, 0xffff0000, v112
	v_fmac_f32_e32 v115, v118, v118
	v_lshlrev_b32_e32 v120, 16, v113
	v_fmac_f32_e32 v115, v119, v119
	v_and_b32_e32 v121, 0xffff0000, v113
	v_fmac_f32_e32 v115, v120, v120
	v_fmac_f32_e32 v115, v121, v121
	flat_store_dwordx4 v[128:129], v[110:113] offset:64
	v_add_f32_e32 v118, v122, v115
	ds_read_b128 v[110:113], v136 offset:160
	ds_read_b128 v[114:117], v136 offset:176
	v_lshlrev_b32_e32 v119, 16, v106
	v_and_b32_e32 v106, 0xffff0000, v106
	s_waitcnt lgkmcnt(0)
	v_add_f32_e32 v110, v110, v119
	v_add_f32_e32 v106, v111, v106
	v_cvt_pk_bf16_f32 v106, v110, v106
	v_lshlrev_b32_e32 v110, 16, v107
	v_and_b32_e32 v107, 0xffff0000, v107
	v_add_f32_e32 v110, v112, v110
	v_add_f32_e32 v107, v113, v107
	v_cvt_pk_bf16_f32 v107, v110, v107
	v_lshlrev_b32_e32 v110, 16, v108
	v_and_b32_e32 v108, 0xffff0000, v108
	v_add_f32_e32 v110, v114, v110
	v_add_f32_e32 v108, v115, v108
	v_cvt_pk_bf16_f32 v108, v110, v108
	v_lshlrev_b32_e32 v110, 16, v109
	v_and_b32_e32 v109, 0xffff0000, v109
	v_add_f32_e32 v110, v116, v110
	v_add_f32_e32 v109, v117, v109
	v_and_b32_e32 v111, 0xffff0000, v106
	v_cvt_pk_bf16_f32 v109, v110, v109
	v_lshlrev_b32_e32 v110, 16, v106
	v_mul_f32_e32 v111, v111, v111
	v_lshlrev_b32_e32 v112, 16, v107
	v_fmac_f32_e32 v111, v110, v110
	v_and_b32_e32 v113, 0xffff0000, v107
	v_fmac_f32_e32 v111, v112, v112
	v_lshlrev_b32_e32 v114, 16, v108
	v_fmac_f32_e32 v111, v113, v113
	v_and_b32_e32 v115, 0xffff0000, v108
	v_fmac_f32_e32 v111, v114, v114
	v_lshlrev_b32_e32 v116, 16, v109
	v_fmac_f32_e32 v111, v115, v115
	v_and_b32_e32 v117, 0xffff0000, v109
	v_fmac_f32_e32 v111, v116, v116
	v_fmac_f32_e32 v111, v117, v117
	flat_store_dwordx4 v[128:129], v[106:109] offset:80
	v_add_f32_e32 v114, v118, v111
	ds_read_b128 v[106:109], v136 offset:192
	ds_read_b128 v[110:113], v136 offset:208
	v_lshlrev_b32_e32 v115, 16, v102
	v_and_b32_e32 v102, 0xffff0000, v102
	s_waitcnt lgkmcnt(0)
	v_add_f32_e32 v106, v106, v115
	v_add_f32_e32 v102, v107, v102
	v_cvt_pk_bf16_f32 v102, v106, v102
	v_lshlrev_b32_e32 v106, 16, v103
	v_and_b32_e32 v103, 0xffff0000, v103
	v_add_f32_e32 v106, v108, v106
	v_add_f32_e32 v103, v109, v103
	v_cvt_pk_bf16_f32 v103, v106, v103
	v_lshlrev_b32_e32 v106, 16, v104
	v_and_b32_e32 v104, 0xffff0000, v104
	v_add_f32_e32 v106, v110, v106
	v_add_f32_e32 v104, v111, v104
	v_cvt_pk_bf16_f32 v104, v106, v104
	v_lshlrev_b32_e32 v106, 16, v105
	v_and_b32_e32 v105, 0xffff0000, v105
	v_add_f32_e32 v106, v112, v106
	v_add_f32_e32 v105, v113, v105
	v_and_b32_e32 v107, 0xffff0000, v102
	v_cvt_pk_bf16_f32 v105, v106, v105
	v_lshlrev_b32_e32 v106, 16, v102
	v_mul_f32_e32 v107, v107, v107
	v_lshlrev_b32_e32 v108, 16, v103
	v_fmac_f32_e32 v107, v106, v106
	v_and_b32_e32 v109, 0xffff0000, v103
	v_fmac_f32_e32 v107, v108, v108
	v_lshlrev_b32_e32 v110, 16, v104
	v_fmac_f32_e32 v107, v109, v109
	v_and_b32_e32 v111, 0xffff0000, v104
	v_fmac_f32_e32 v107, v110, v110
	v_lshlrev_b32_e32 v112, 16, v105
	v_fmac_f32_e32 v107, v111, v111
	v_and_b32_e32 v113, 0xffff0000, v105
	v_fmac_f32_e32 v107, v112, v112
	v_fmac_f32_e32 v107, v113, v113
	flat_store_dwordx4 v[128:129], v[102:105] offset:96
	v_add_f32_e32 v110, v114, v107
	ds_read_b128 v[102:105], v136 offset:224
	ds_read_b128 v[106:109], v136 offset:240
	v_lshlrev_b32_e32 v111, 16, v98
	v_and_b32_e32 v98, 0xffff0000, v98
	s_waitcnt lgkmcnt(0)
	v_add_f32_e32 v102, v102, v111
	v_add_f32_e32 v98, v103, v98
	v_cvt_pk_bf16_f32 v98, v102, v98
	v_lshlrev_b32_e32 v102, 16, v99
	v_and_b32_e32 v99, 0xffff0000, v99
	v_add_f32_e32 v102, v104, v102
	v_add_f32_e32 v99, v105, v99
	v_cvt_pk_bf16_f32 v99, v102, v99
	v_lshlrev_b32_e32 v102, 16, v100
	v_and_b32_e32 v100, 0xffff0000, v100
	v_add_f32_e32 v102, v106, v102
	v_add_f32_e32 v100, v107, v100
	v_cvt_pk_bf16_f32 v100, v102, v100
	v_lshlrev_b32_e32 v102, 16, v101
	v_and_b32_e32 v101, 0xffff0000, v101
	v_add_f32_e32 v102, v108, v102
	v_add_f32_e32 v101, v109, v101
	v_and_b32_e32 v103, 0xffff0000, v98
	v_cvt_pk_bf16_f32 v101, v102, v101
	v_lshlrev_b32_e32 v102, 16, v98
	v_mul_f32_e32 v103, v103, v103
	v_lshlrev_b32_e32 v104, 16, v99
	v_fmac_f32_e32 v103, v102, v102
	v_and_b32_e32 v105, 0xffff0000, v99
	v_fmac_f32_e32 v103, v104, v104
	v_lshlrev_b32_e32 v106, 16, v100
	v_fmac_f32_e32 v103, v105, v105
	v_and_b32_e32 v107, 0xffff0000, v100
	v_fmac_f32_e32 v103, v106, v106
	v_lshlrev_b32_e32 v108, 16, v101
	v_fmac_f32_e32 v103, v107, v107
	v_and_b32_e32 v109, 0xffff0000, v101
	v_fmac_f32_e32 v103, v108, v108
	flat_store_dwordx4 v[128:129], v[98:101] offset:112
	v_fmac_f32_e32 v103, v109, v109
	v_add_f32_e32 v102, v110, v103
	v_lshlrev_b64 v[98:99], 6, v[126:127]
	v_lshl_add_u64 v[98:99], s[6:7], 0, v[98:99]
	v_lshl_add_u64 v[98:99], v[98:99], 0, s[16:17]
	flat_store_dword v[98:99], v102
	s_waitcnt lgkmcnt(0)
	s_barrier
	ds_write2_b32 v1, v62, v74 offset1:16
	ds_write2_b32 v1, v63, v75 offset0:68 offset1:84
	ds_write2_b32 v1, v64, v76 offset0:136 offset1:152
	ds_write2_b32 v1, v65, v77 offset0:204 offset1:220
	ds_write2_b32 v1, v78, v82 offset0:32 offset1:48
	ds_write2_b32 v1, v79, v83 offset0:100 offset1:116
	ds_write2_b32 v1, v80, v84 offset0:168 offset1:184
	ds_write2_b32 v1, v81, v85 offset0:236 offset1:252
	ds_write2_b32 v130, v46, v54 offset0:64 offset1:80
	ds_write2_b32 v130, v47, v55 offset0:132 offset1:148
	ds_write2_b32 v130, v48, v56 offset0:200 offset1:216
	ds_write2_b32 v131, v49, v57 offset0:12 offset1:28
	ds_write2_b32 v130, v58, v66 offset0:96 offset1:112
	ds_write2_b32 v130, v59, v67 offset0:164 offset1:180
	ds_write2_b32 v130, v60, v68 offset0:232 offset1:248
	ds_write2_b32 v131, v61, v69 offset0:44 offset1:60
	ds_write2_b32 v132, v30, v38 offset0:128 offset1:144
	ds_write2_b32 v132, v31, v39 offset0:196 offset1:212
	ds_write2_b32 v133, v32, v40 offset0:8 offset1:24
	ds_write2_b32 v133, v33, v41 offset0:76 offset1:92
	ds_write2_b32 v132, v42, v50 offset0:160 offset1:176
	ds_write2_b32 v132, v43, v51 offset0:228 offset1:244
	ds_write2_b32 v133, v44, v52 offset0:40 offset1:56
	ds_write2_b32 v133, v45, v53 offset0:108 offset1:124
	ds_write2_b32 v135, v18, v22 offset0:192 offset1:208
	ds_write2_b32 v134, v19, v23 offset0:4 offset1:20
	ds_write2_b32 v134, v20, v24 offset0:72 offset1:88
	ds_write2_b32 v134, v21, v25 offset0:140 offset1:156
	ds_write2_b32 v135, v26, v34 offset0:224 offset1:240
	ds_write2_b32 v134, v27, v35 offset0:36 offset1:52
	ds_write2_b32 v134, v28, v36 offset0:104 offset1:120
	ds_write2_b32 v134, v29, v37 offset0:172 offset1:188
	v_mov_b32_e32 v1, v170
	s_waitcnt lgkmcnt(0)
	s_barrier
	s_waitcnt vmcnt(0)
	v_lshlrev_b32_e32 v28, 16, v94
	v_add_u32_e32 v18, s4, v1
	v_ashrrev_i32_e32 v19, 31, v18
	v_lshlrev_b64 v[20:21], 11, v[18:19]
	v_lshl_add_u64 v[20:21], s[38:39], 0, v[20:21]
	v_mul_lo_u32 v1, v1, s33
	v_lshl_add_u64 v[32:33], v[20:21], 0, s[18:19]
	ds_read_b128 v[20:23], v1
	ds_read_b128 v[24:27], v1 offset:16
	s_mov_b64 s[4:5], 0
	s_waitcnt lgkmcnt(1)
	v_add_f32_e32 v20, v20, v28
	v_and_b32_e32 v28, 0xffff0000, v94
	v_add_f32_e32 v21, v21, v28
	v_cvt_pk_bf16_f32 v28, v20, v21
	v_and_b32_e32 v21, 0xffff0000, v95
	v_lshlrev_b32_e32 v20, 16, v95
	v_add_f32_e32 v21, v23, v21
	v_add_f32_e32 v20, v22, v20
	v_cvt_pk_bf16_f32 v29, v20, v21
	v_and_b32_e32 v21, 0xffff0000, v96
	v_lshlrev_b32_e32 v20, 16, v96
	s_waitcnt lgkmcnt(0)
	v_add_f32_e32 v21, v25, v21
	v_add_f32_e32 v20, v24, v20
	v_cvt_pk_bf16_f32 v30, v20, v21
	v_and_b32_e32 v21, 0xffff0000, v97
	v_lshlrev_b32_e32 v20, 16, v97
	v_add_f32_e32 v21, v27, v21
	v_add_f32_e32 v20, v26, v20
	v_cvt_pk_bf16_f32 v31, v20, v21
	v_and_b32_e32 v21, 0xffff0000, v28
	v_lshlrev_b32_e32 v20, 16, v28
	v_mul_f32_e32 v34, v21, v21
	v_lshlrev_b32_e32 v22, 16, v29
	v_fmac_f32_e32 v34, v20, v20
	v_and_b32_e32 v23, 0xffff0000, v29
	v_fmac_f32_e32 v34, v22, v22
	v_lshlrev_b32_e32 v24, 16, v30
	v_fmac_f32_e32 v34, v23, v23
	v_and_b32_e32 v25, 0xffff0000, v30
	v_fmac_f32_e32 v34, v24, v24
	v_add_co_u32_e32 v20, vcc, s90, v32
	v_lshlrev_b32_e32 v26, 16, v31
	v_fmac_f32_e32 v34, v25, v25
	v_addc_co_u32_e32 v21, vcc, 0, v33, vcc
	v_and_b32_e32 v27, 0xffff0000, v31
	v_fmac_f32_e32 v34, v26, v26
	flat_store_dwordx4 v[20:21], v[28:31] offset:128
	v_fmac_f32_e32 v34, v27, v27
	ds_read_b128 v[22:25], v1 offset:32
	ds_read_b128 v[26:29], v1 offset:48
	v_lshlrev_b32_e32 v30, 16, v90
	s_waitcnt lgkmcnt(0)
	v_add_f32_e32 v22, v22, v30
	v_and_b32_e32 v30, 0xffff0000, v90
	v_add_f32_e32 v23, v23, v30
	v_cvt_pk_bf16_f32 v22, v22, v23
	v_lshlrev_b32_e32 v23, 16, v91
	v_add_f32_e32 v23, v24, v23
	v_and_b32_e32 v24, 0xffff0000, v91
	v_add_f32_e32 v24, v25, v24
	v_cvt_pk_bf16_f32 v23, v23, v24
	v_lshlrev_b32_e32 v24, 16, v92
	v_and_b32_e32 v25, 0xffff0000, v92
	v_add_f32_e32 v24, v26, v24
	v_add_f32_e32 v25, v27, v25
	v_cvt_pk_bf16_f32 v24, v24, v25
	v_lshlrev_b32_e32 v25, 16, v93
	v_and_b32_e32 v26, 0xffff0000, v93
	v_add_f32_e32 v25, v28, v25
	v_add_f32_e32 v26, v29, v26
	v_and_b32_e32 v27, 0xffff0000, v22
	v_cvt_pk_bf16_f32 v25, v25, v26
	v_lshlrev_b32_e32 v26, 16, v22
	v_mul_f32_e32 v27, v27, v27
	v_lshlrev_b32_e32 v28, 16, v23
	v_fmac_f32_e32 v27, v26, v26
	v_and_b32_e32 v29, 0xffff0000, v23
	v_fmac_f32_e32 v27, v28, v28
	v_lshlrev_b32_e32 v30, 16, v24
	v_fmac_f32_e32 v27, v29, v29
	v_and_b32_e32 v31, 0xffff0000, v24
	v_fmac_f32_e32 v27, v30, v30
	v_lshlrev_b32_e32 v32, 16, v25
	v_fmac_f32_e32 v27, v31, v31
	v_and_b32_e32 v33, 0xffff0000, v25
	v_fmac_f32_e32 v27, v32, v32
	v_fmac_f32_e32 v27, v33, v33
	flat_store_dwordx4 v[20:21], v[22:25] offset:144
	v_add_f32_e32 v30, v34, v27
	ds_read_b128 v[22:25], v1 offset:64
	ds_read_b128 v[26:29], v1 offset:80
	v_lshlrev_b32_e32 v31, 16, v86
	s_waitcnt lgkmcnt(0)
	v_add_f32_e32 v22, v22, v31
	v_and_b32_e32 v31, 0xffff0000, v86
	v_add_f32_e32 v23, v23, v31
	v_cvt_pk_bf16_f32 v22, v22, v23
	v_lshlrev_b32_e32 v23, 16, v87
	v_add_f32_e32 v23, v24, v23
	v_and_b32_e32 v24, 0xffff0000, v87
	v_add_f32_e32 v24, v25, v24
	v_cvt_pk_bf16_f32 v23, v23, v24
	v_lshlrev_b32_e32 v24, 16, v88
	v_and_b32_e32 v25, 0xffff0000, v88
	v_add_f32_e32 v24, v26, v24
	v_add_f32_e32 v25, v27, v25
	v_cvt_pk_bf16_f32 v24, v24, v25
	v_lshlrev_b32_e32 v25, 16, v89
	v_and_b32_e32 v26, 0xffff0000, v89
	v_add_f32_e32 v25, v28, v25
	v_add_f32_e32 v26, v29, v26
	v_and_b32_e32 v27, 0xffff0000, v22
	v_cvt_pk_bf16_f32 v25, v25, v26
	v_lshlrev_b32_e32 v26, 16, v22
	v_mul_f32_e32 v27, v27, v27
	v_lshlrev_b32_e32 v28, 16, v23
	v_fmac_f32_e32 v27, v26, v26
	v_and_b32_e32 v29, 0xffff0000, v23
	v_fmac_f32_e32 v27, v28, v28
	v_lshlrev_b32_e32 v31, 16, v24
	v_fmac_f32_e32 v27, v29, v29
	v_and_b32_e32 v32, 0xffff0000, v24
	v_fmac_f32_e32 v27, v31, v31
	v_lshlrev_b32_e32 v33, 16, v25
	v_fmac_f32_e32 v27, v32, v32
	v_and_b32_e32 v34, 0xffff0000, v25
	v_fmac_f32_e32 v27, v33, v33
	v_fmac_f32_e32 v27, v34, v34
	flat_store_dwordx4 v[20:21], v[22:25] offset:160
	v_add_f32_e32 v30, v30, v27
	ds_read_b128 v[22:25], v1 offset:96
	ds_read_b128 v[26:29], v1 offset:112
	v_lshlrev_b32_e32 v31, 16, v70
	s_waitcnt lgkmcnt(0)
	v_add_f32_e32 v22, v22, v31
	v_and_b32_e32 v31, 0xffff0000, v70
	v_add_f32_e32 v23, v23, v31
	v_cvt_pk_bf16_f32 v22, v22, v23
	v_lshlrev_b32_e32 v23, 16, v71
	v_add_f32_e32 v23, v24, v23
	v_and_b32_e32 v24, 0xffff0000, v71
	v_add_f32_e32 v24, v25, v24
	v_cvt_pk_bf16_f32 v23, v23, v24
	v_lshlrev_b32_e32 v24, 16, v72
	v_and_b32_e32 v25, 0xffff0000, v72
	v_add_f32_e32 v24, v26, v24
	v_add_f32_e32 v25, v27, v25
	v_cvt_pk_bf16_f32 v24, v24, v25
	v_lshlrev_b32_e32 v25, 16, v73
	v_and_b32_e32 v26, 0xffff0000, v73
	v_add_f32_e32 v25, v28, v25
	v_add_f32_e32 v26, v29, v26
	v_and_b32_e32 v27, 0xffff0000, v22
	v_cvt_pk_bf16_f32 v25, v25, v26
	v_lshlrev_b32_e32 v26, 16, v22
	v_mul_f32_e32 v27, v27, v27
	v_lshlrev_b32_e32 v28, 16, v23
	v_fmac_f32_e32 v27, v26, v26
	v_and_b32_e32 v29, 0xffff0000, v23
	v_fmac_f32_e32 v27, v28, v28
	v_lshlrev_b32_e32 v31, 16, v24
	v_fmac_f32_e32 v27, v29, v29
	v_and_b32_e32 v32, 0xffff0000, v24
	v_fmac_f32_e32 v27, v31, v31
	v_lshlrev_b32_e32 v33, 16, v25
	v_fmac_f32_e32 v27, v32, v32
	v_and_b32_e32 v34, 0xffff0000, v25
	v_fmac_f32_e32 v27, v33, v33
	v_fmac_f32_e32 v27, v34, v34
	flat_store_dwordx4 v[20:21], v[22:25] offset:176
	v_add_f32_e32 v30, v30, v27
	ds_read_b128 v[22:25], v1 offset:128
	ds_read_b128 v[26:29], v1 offset:144
	v_lshlrev_b32_e32 v31, 16, v14
	v_and_b32_e32 v14, 0xffff0000, v14
	s_waitcnt lgkmcnt(0)
	v_add_f32_e32 v22, v22, v31
	v_add_f32_e32 v14, v23, v14
	v_cvt_pk_bf16_f32 v14, v22, v14
	v_lshlrev_b32_e32 v22, 16, v15
	v_and_b32_e32 v15, 0xffff0000, v15
	v_add_f32_e32 v22, v24, v22
	v_add_f32_e32 v15, v25, v15
	v_cvt_pk_bf16_f32 v15, v22, v15
	v_lshlrev_b32_e32 v22, 16, v16
	v_and_b32_e32 v16, 0xffff0000, v16
	v_add_f32_e32 v22, v26, v22
	v_add_f32_e32 v16, v27, v16
	v_cvt_pk_bf16_f32 v16, v22, v16
	v_lshlrev_b32_e32 v22, 16, v17
	v_and_b32_e32 v17, 0xffff0000, v17
	v_add_f32_e32 v22, v28, v22
	v_add_f32_e32 v17, v29, v17
	v_and_b32_e32 v23, 0xffff0000, v14
	v_cvt_pk_bf16_f32 v17, v22, v17
	v_lshlrev_b32_e32 v22, 16, v14
	v_mul_f32_e32 v23, v23, v23
	v_lshlrev_b32_e32 v24, 16, v15
	v_fmac_f32_e32 v23, v22, v22
	v_and_b32_e32 v25, 0xffff0000, v15
	v_fmac_f32_e32 v23, v24, v24
	v_lshlrev_b32_e32 v26, 16, v16
	v_fmac_f32_e32 v23, v25, v25
	v_and_b32_e32 v27, 0xffff0000, v16
	v_fmac_f32_e32 v23, v26, v26
	v_lshlrev_b32_e32 v28, 16, v17
	v_fmac_f32_e32 v23, v27, v27
	v_and_b32_e32 v29, 0xffff0000, v17
	v_fmac_f32_e32 v23, v28, v28
	v_fmac_f32_e32 v23, v29, v29
	flat_store_dwordx4 v[20:21], v[14:17] offset:192
	v_add_f32_e32 v26, v30, v23
	ds_read_b128 v[14:17], v1 offset:160
	ds_read_b128 v[22:25], v1 offset:176
	v_lshlrev_b32_e32 v27, 16, v10
	v_and_b32_e32 v10, 0xffff0000, v10
	s_waitcnt lgkmcnt(0)
	v_add_f32_e32 v14, v14, v27
	v_add_f32_e32 v10, v15, v10
	v_cvt_pk_bf16_f32 v10, v14, v10
	v_lshlrev_b32_e32 v14, 16, v11
	v_and_b32_e32 v11, 0xffff0000, v11
	v_add_f32_e32 v14, v16, v14
	v_add_f32_e32 v11, v17, v11
	v_cvt_pk_bf16_f32 v11, v14, v11
	v_lshlrev_b32_e32 v14, 16, v12
	v_and_b32_e32 v12, 0xffff0000, v12
	v_add_f32_e32 v14, v22, v14
	v_add_f32_e32 v12, v23, v12
	v_cvt_pk_bf16_f32 v12, v14, v12
	v_lshlrev_b32_e32 v14, 16, v13
	v_and_b32_e32 v13, 0xffff0000, v13
	v_add_f32_e32 v14, v24, v14
	v_add_f32_e32 v13, v25, v13
	v_and_b32_e32 v15, 0xffff0000, v10
	v_cvt_pk_bf16_f32 v13, v14, v13
	v_lshlrev_b32_e32 v14, 16, v10
	v_mul_f32_e32 v15, v15, v15
	v_lshlrev_b32_e32 v16, 16, v11
	v_fmac_f32_e32 v15, v14, v14
	v_and_b32_e32 v17, 0xffff0000, v11
	v_fmac_f32_e32 v15, v16, v16
	v_lshlrev_b32_e32 v22, 16, v12
	v_fmac_f32_e32 v15, v17, v17
	v_and_b32_e32 v23, 0xffff0000, v12
	v_fmac_f32_e32 v15, v22, v22
	v_lshlrev_b32_e32 v24, 16, v13
	v_fmac_f32_e32 v15, v23, v23
	v_and_b32_e32 v25, 0xffff0000, v13
	v_fmac_f32_e32 v15, v24, v24
	v_fmac_f32_e32 v15, v25, v25
	flat_store_dwordx4 v[20:21], v[10:13] offset:208
	v_add_f32_e32 v22, v26, v15
	ds_read_b128 v[10:13], v1 offset:192
	ds_read_b128 v[14:17], v1 offset:208
	v_lshlrev_b32_e32 v23, 16, v6
	v_and_b32_e32 v6, 0xffff0000, v6
	s_waitcnt lgkmcnt(0)
	v_add_f32_e32 v10, v10, v23
	v_add_f32_e32 v6, v11, v6
	v_cvt_pk_bf16_f32 v6, v10, v6
	v_lshlrev_b32_e32 v10, 16, v7
	v_and_b32_e32 v7, 0xffff0000, v7
	v_add_f32_e32 v10, v12, v10
	v_add_f32_e32 v7, v13, v7
	v_cvt_pk_bf16_f32 v7, v10, v7
	v_lshlrev_b32_e32 v10, 16, v8
	v_and_b32_e32 v8, 0xffff0000, v8
	v_add_f32_e32 v10, v14, v10
	v_add_f32_e32 v8, v15, v8
	v_cvt_pk_bf16_f32 v8, v10, v8
	v_lshlrev_b32_e32 v10, 16, v9
	v_and_b32_e32 v9, 0xffff0000, v9
	v_add_f32_e32 v10, v16, v10
	v_add_f32_e32 v9, v17, v9
	v_and_b32_e32 v11, 0xffff0000, v6
	v_cvt_pk_bf16_f32 v9, v10, v9
	v_lshlrev_b32_e32 v10, 16, v6
	v_mul_f32_e32 v11, v11, v11
	v_lshlrev_b32_e32 v12, 16, v7
	v_fmac_f32_e32 v11, v10, v10
	v_and_b32_e32 v13, 0xffff0000, v7
	v_fmac_f32_e32 v11, v12, v12
	v_lshlrev_b32_e32 v14, 16, v8
	v_fmac_f32_e32 v11, v13, v13
	v_and_b32_e32 v15, 0xffff0000, v8
	v_fmac_f32_e32 v11, v14, v14
	v_lshlrev_b32_e32 v16, 16, v9
	v_fmac_f32_e32 v11, v15, v15
	v_and_b32_e32 v17, 0xffff0000, v9
	v_fmac_f32_e32 v11, v16, v16
	v_fmac_f32_e32 v11, v17, v17
	flat_store_dwordx4 v[20:21], v[6:9] offset:224
	v_add_f32_e32 v14, v22, v11
	ds_read_b128 v[6:9], v1 offset:224
	ds_read_b128 v[10:13], v1 offset:240
	v_lshlrev_b32_e32 v1, 16, v2
	v_and_b32_e32 v2, 0xffff0000, v2
	s_waitcnt lgkmcnt(0)
	v_add_f32_e32 v1, v6, v1
	v_add_f32_e32 v2, v7, v2
	v_cvt_pk_bf16_f32 v2, v1, v2
	v_lshlrev_b32_e32 v1, 16, v3
	v_and_b32_e32 v3, 0xffff0000, v3
	v_add_f32_e32 v1, v8, v1
	v_add_f32_e32 v3, v9, v3
	v_cvt_pk_bf16_f32 v3, v1, v3
	v_lshlrev_b32_e32 v1, 16, v4
	v_and_b32_e32 v4, 0xffff0000, v4
	v_add_f32_e32 v1, v10, v1
	v_add_f32_e32 v4, v11, v4
	v_cvt_pk_bf16_f32 v4, v1, v4
	v_lshlrev_b32_e32 v1, 16, v5
	v_and_b32_e32 v5, 0xffff0000, v5
	v_add_f32_e32 v1, v12, v1
	v_add_f32_e32 v5, v13, v5
	v_and_b32_e32 v6, 0xffff0000, v2
	v_cvt_pk_bf16_f32 v5, v1, v5
	v_lshlrev_b32_e32 v1, 16, v2
	v_mul_f32_e32 v6, v6, v6
	v_lshlrev_b32_e32 v7, 16, v3
	v_fmac_f32_e32 v6, v1, v1
	v_and_b32_e32 v8, 0xffff0000, v3
	v_fmac_f32_e32 v6, v7, v7
	v_lshlrev_b32_e32 v9, 16, v4
	v_fmac_f32_e32 v6, v8, v8
	v_and_b32_e32 v10, 0xffff0000, v4
	v_fmac_f32_e32 v6, v9, v9
	v_lshlrev_b32_e32 v11, 16, v5
	v_fmac_f32_e32 v6, v10, v10
	v_and_b32_e32 v12, 0xffff0000, v5
	v_fmac_f32_e32 v6, v11, v11
	flat_store_dwordx4 v[20:21], v[2:5] offset:240
	v_fmac_f32_e32 v6, v12, v12
	v_add_f32_e32 v1, v14, v6
	v_lshlrev_b64 v[2:3], 6, v[18:19]
	v_lshl_add_u64 v[2:3], s[6:7], 0, v[2:3]
	v_lshl_add_u64 v[2:3], v[2:3], 0, s[16:17]
	flat_store_dword v[2:3], v1 offset:4
	s_branch .LBB0_522

.Lbk64_557:
	s_waitcnt vmcnt(0)
	s_barrier
	ds_read_b128 v[192:195], v243
	ds_read_b128 v[196:199], v244
	ds_read_b128 v[200:203], v243 offset:2048
	ds_read_b128 v[204:207], v244 offset:2048
	ds_read_b128 v[208:211], v243 offset:4096
	ds_read_b128 v[212:215], v244 offset:4096
	ds_read_b128 v[216:219], v243 offset:6144
	ds_read_b128 v[220:223], v244 offset:6144
	s_add_u32 s4, s4, 0x80
	s_addc_u32 s5, s5, 0
	s_add_u32 s6, s6, 0x80
	s_addc_u32 s7, s7, 0
	s_waitcnt lgkmcnt(0)
	ds_read_b128 v[224:227], v245 offset:0
	ds_read_b128 v[228:231], v246 offset:0
	ds_read_b128 v[232:235], v245 offset:2048
	ds_read_b128 v[236:239], v246 offset:2048
	s_waitcnt lgkmcnt(2)
	v_mfma_f32_16x16x32_bf16 v[142:145], v[192:195], v[224:227], v[142:145]
	v_mfma_f32_16x16x32_bf16 v[130:133], v[200:203], v[224:227], v[130:133]
	v_mfma_f32_16x16x32_bf16 v[110:113], v[208:211], v[224:227], v[110:113]
	v_mfma_f32_16x16x32_bf16 v[78:81], v[216:219], v[224:227], v[78:81]
	v_readfirstlane_b32 s32, v153
	s_lshl_b32 m0, s32, 3
	v_mov_b32_e32 v242, v240
	global_load_lds_dwordx4 v242, s[4:5]
	v_mfma_f32_16x16x32_bf16 v[142:145], v[196:199], v[228:231], v[142:145]
	v_mfma_f32_16x16x32_bf16 v[130:133], v[204:207], v[228:231], v[130:133]
	v_mfma_f32_16x16x32_bf16 v[110:113], v[212:215], v[228:231], v[110:113]
	v_mfma_f32_16x16x32_bf16 v[78:81], v[220:223], v[228:231], v[78:81]
	s_add_u32 m0, m0, 0x400
	v_add_u32_e32 v242, 0x4000, v240
	global_load_lds_dwordx4 v242, s[4:5]
	ds_read_b128 v[224:227], v245 offset:4096
	ds_read_b128 v[228:231], v246 offset:4096
	s_waitcnt lgkmcnt(2)
	v_mfma_f32_16x16x32_bf16 v[138:141], v[192:195], v[232:235], v[138:141]
	v_mfma_f32_16x16x32_bf16 v[122:125], v[200:203], v[232:235], v[122:125]
	v_mfma_f32_16x16x32_bf16 v[94:97], v[208:211], v[232:235], v[94:97]
	v_mfma_f32_16x16x32_bf16 v[62:65], v[216:219], v[232:235], v[62:65]
	s_add_u32 m0, m0, 0x400
	v_add_u32_e32 v242, 0x8000, v240
	global_load_lds_dwordx4 v242, s[4:5]
	v_mfma_f32_16x16x32_bf16 v[138:141], v[196:199], v[236:239], v[138:141]
	v_mfma_f32_16x16x32_bf16 v[122:125], v[204:207], v[236:239], v[122:125]
	v_mfma_f32_16x16x32_bf16 v[94:97], v[212:215], v[236:239], v[94:97]
	v_mfma_f32_16x16x32_bf16 v[62:65], v[220:223], v[236:239], v[62:65]
	s_add_u32 m0, m0, 0x400
	v_add_u32_e32 v242, 0xc000, v240
	global_load_lds_dwordx4 v242, s[4:5]
	ds_read_b128 v[232:235], v245 offset:6144
	ds_read_b128 v[236:239], v246 offset:6144
	s_waitcnt lgkmcnt(2)
	v_mfma_f32_16x16x32_bf16 v[134:137], v[192:195], v[224:227], v[134:137]
	v_mfma_f32_16x16x32_bf16 v[114:117], v[200:203], v[224:227], v[114:117]
	v_mfma_f32_16x16x32_bf16 v[86:89], v[208:211], v[224:227], v[86:89]
	v_mfma_f32_16x16x32_bf16 v[54:57], v[216:219], v[224:227], v[54:57]
	s_add_u32 m0, m0, 0x400
	v_add_u32_e32 v242, 0x10000, v240
	global_load_lds_dwordx4 v242, s[4:5]
	v_mfma_f32_16x16x32_bf16 v[134:137], v[196:199], v[228:231], v[134:137]
	v_mfma_f32_16x16x32_bf16 v[114:117], v[204:207], v[228:231], v[114:117]
	v_mfma_f32_16x16x32_bf16 v[86:89], v[212:215], v[228:231], v[86:89]
	v_mfma_f32_16x16x32_bf16 v[54:57], v[220:223], v[228:231], v[54:57]
	s_add_u32 m0, m0, 0x400
	v_add_u32_e32 v242, 0x14000, v240
	global_load_lds_dwordx4 v242, s[4:5]
	ds_read_b128 v[224:227], v245 offset:8192
	ds_read_b128 v[228:231], v246 offset:8192
	s_waitcnt lgkmcnt(2)
	v_mfma_f32_16x16x32_bf16 v[126:129], v[192:195], v[232:235], v[126:129]
	v_mfma_f32_16x16x32_bf16 v[102:105], v[200:203], v[232:235], v[102:105]
	v_mfma_f32_16x16x32_bf16 v[70:73], v[208:211], v[232:235], v[70:73]
	v_mfma_f32_16x16x32_bf16 v[42:45], v[216:219], v[232:235], v[42:45]
	s_add_u32 m0, m0, 0x400
	v_add_u32_e32 v242, 0x18000, v240
	global_load_lds_dwordx4 v242, s[4:5]
	v_mfma_f32_16x16x32_bf16 v[126:129], v[196:199], v[236:239], v[126:129]
	v_mfma_f32_16x16x32_bf16 v[102:105], v[204:207], v[236:239], v[102:105]
	v_mfma_f32_16x16x32_bf16 v[70:73], v[212:215], v[236:239], v[70:73]
	v_mfma_f32_16x16x32_bf16 v[42:45], v[220:223], v[236:239], v[42:45]
	s_add_u32 m0, m0, 0x400
	v_add_u32_e32 v242, 0x1c000, v240
	global_load_lds_dwordx4 v242, s[4:5]
	ds_read_b128 v[232:235], v245 offset:10240
	ds_read_b128 v[236:239], v246 offset:10240
	s_waitcnt lgkmcnt(2)
	v_mfma_f32_16x16x32_bf16 v[118:121], v[192:195], v[224:227], v[118:121]
	v_mfma_f32_16x16x32_bf16 v[90:93], v[200:203], v[224:227], v[90:93]
	v_mfma_f32_16x16x32_bf16 v[58:61], v[208:211], v[224:227], v[58:61]
	v_mfma_f32_16x16x32_bf16 v[34:37], v[216:219], v[224:227], v[34:37]
	s_add_u32 m0, s31, 17
	s_and_b32 m0, m0, 1
	s_lshl_b32 m0, m0, 14
	s_add_u32 m0, m0, 0x8000
	v_readfirstlane_b32 s32, v153
	s_lshl_b32 s32, s32, 2
	s_add_u32 m0, m0, s32
	v_mov_b32_e32 v242, v241
	global_load_lds_dwordx4 v242, s[6:7]
	v_mfma_f32_16x16x32_bf16 v[118:121], v[196:199], v[228:231], v[118:121]
	v_mfma_f32_16x16x32_bf16 v[90:93], v[204:207], v[228:231], v[90:93]
	v_mfma_f32_16x16x32_bf16 v[58:61], v[212:215], v[228:231], v[58:61]
	v_mfma_f32_16x16x32_bf16 v[34:37], v[220:223], v[228:231], v[34:37]
	s_add_u32 m0, m0, 0x400
	v_add_u32_e32 v242, 0x4000, v241
	global_load_lds_dwordx4 v242, s[6:7]
	ds_read_b128 v[224:227], v245 offset:12288
	ds_read_b128 v[228:231], v246 offset:12288
	s_waitcnt lgkmcnt(2)
	v_mfma_f32_16x16x32_bf16 v[106:109], v[192:195], v[232:235], v[106:109]
	v_mfma_f32_16x16x32_bf16 v[74:77], v[200:203], v[232:235], v[74:77]
	v_mfma_f32_16x16x32_bf16 v[46:49], v[208:211], v[232:235], v[46:49]
	v_mfma_f32_16x16x32_bf16 v[26:29], v[216:219], v[232:235], v[26:29]
	s_add_u32 m0, m0, 0x400
	v_add_u32_e32 v242, 0x8000, v241
	global_load_lds_dwordx4 v242, s[6:7]
	v_mfma_f32_16x16x32_bf16 v[106:109], v[196:199], v[236:239], v[106:109]
	v_mfma_f32_16x16x32_bf16 v[74:77], v[204:207], v[236:239], v[74:77]
	v_mfma_f32_16x16x32_bf16 v[46:49], v[212:215], v[236:239], v[46:49]
	v_mfma_f32_16x16x32_bf16 v[26:29], v[220:223], v[236:239], v[26:29]
	s_add_u32 m0, m0, 0x400
	v_add_u32_e32 v242, 0xc000, v241
	global_load_lds_dwordx4 v242, s[6:7]
	ds_read_b128 v[232:235], v245 offset:14336
	ds_read_b128 v[236:239], v246 offset:14336
	s_waitcnt lgkmcnt(2)
	v_mfma_f32_16x16x32_bf16 v[98:101], v[192:195], v[224:227], v[98:101]
	v_mfma_f32_16x16x32_bf16 v[66:69], v[200:203], v[224:227], v[66:69]
	v_mfma_f32_16x16x32_bf16 v[38:41], v[208:211], v[224:227], v[38:41]
	v_mfma_f32_16x16x32_bf16 v[22:25], v[216:219], v[224:227], v[22:25]
	v_mfma_f32_16x16x32_bf16 v[98:101], v[196:199], v[228:231], v[98:101]
	v_mfma_f32_16x16x32_bf16 v[66:69], v[204:207], v[228:231], v[66:69]
	v_mfma_f32_16x16x32_bf16 v[38:41], v[212:215], v[228:231], v[38:41]
	v_mfma_f32_16x16x32_bf16 v[22:25], v[220:223], v[228:231], v[22:25]
	s_waitcnt lgkmcnt(0)
	v_mfma_f32_16x16x32_bf16 v[82:85], v[192:195], v[232:235], v[82:85]
	v_mfma_f32_16x16x32_bf16 v[50:53], v[200:203], v[232:235], v[50:53]
	v_mfma_f32_16x16x32_bf16 v[30:33], v[208:211], v[232:235], v[30:33]
	v_mfma_f32_16x16x32_bf16 v[18:21], v[216:219], v[232:235], v[18:21]
	v_mfma_f32_16x16x32_bf16 v[82:85], v[196:199], v[236:239], v[82:85]
	v_mfma_f32_16x16x32_bf16 v[50:53], v[204:207], v[236:239], v[50:53]
	v_mfma_f32_16x16x32_bf16 v[30:33], v[212:215], v[236:239], v[30:33]
	v_mfma_f32_16x16x32_bf16 v[18:21], v[220:223], v[236:239], v[18:21]
	v_xor_b32_e32 v245, 0x4000, v245
	v_xor_b32_e32 v246, 0x4000, v246
	s_add_i32 s31, s31, 1
	s_cmp_lg_u32 s31, 15
	s_cbranch_scc1 .Lbk64_557
	s_waitcnt vmcnt(0)
	s_barrier
	ds_read_b128 v[192:195], v243
	ds_read_b128 v[196:199], v244
	ds_read_b128 v[200:203], v243 offset:2048
	ds_read_b128 v[204:207], v244 offset:2048
	ds_read_b128 v[208:211], v243 offset:4096
	ds_read_b128 v[212:215], v244 offset:4096
	ds_read_b128 v[216:219], v243 offset:6144
	ds_read_b128 v[220:223], v244 offset:6144
	s_waitcnt lgkmcnt(0)
	ds_read_b128 v[224:227], v245 offset:0
	ds_read_b128 v[228:231], v246 offset:0
	ds_read_b128 v[232:235], v245 offset:2048
	ds_read_b128 v[236:239], v246 offset:2048
	s_waitcnt lgkmcnt(2)
	v_mfma_f32_16x16x32_bf16 v[142:145], v[192:195], v[224:227], v[142:145]
	v_mfma_f32_16x16x32_bf16 v[130:133], v[200:203], v[224:227], v[130:133]
	v_mfma_f32_16x16x32_bf16 v[110:113], v[208:211], v[224:227], v[110:113]
	v_mfma_f32_16x16x32_bf16 v[78:81], v[216:219], v[224:227], v[78:81]
	v_mfma_f32_16x16x32_bf16 v[142:145], v[196:199], v[228:231], v[142:145]
	v_mfma_f32_16x16x32_bf16 v[130:133], v[204:207], v[228:231], v[130:133]
	v_mfma_f32_16x16x32_bf16 v[110:113], v[212:215], v[228:231], v[110:113]
	v_mfma_f32_16x16x32_bf16 v[78:81], v[220:223], v[228:231], v[78:81]
	ds_read_b128 v[224:227], v245 offset:4096
	ds_read_b128 v[228:231], v246 offset:4096
	s_waitcnt lgkmcnt(2)
	v_mfma_f32_16x16x32_bf16 v[138:141], v[192:195], v[232:235], v[138:141]
	v_mfma_f32_16x16x32_bf16 v[122:125], v[200:203], v[232:235], v[122:125]
	v_mfma_f32_16x16x32_bf16 v[94:97], v[208:211], v[232:235], v[94:97]
	v_mfma_f32_16x16x32_bf16 v[62:65], v[216:219], v[232:235], v[62:65]
	v_mfma_f32_16x16x32_bf16 v[138:141], v[196:199], v[236:239], v[138:141]
	v_mfma_f32_16x16x32_bf16 v[122:125], v[204:207], v[236:239], v[122:125]
	v_mfma_f32_16x16x32_bf16 v[94:97], v[212:215], v[236:239], v[94:97]
	v_mfma_f32_16x16x32_bf16 v[62:65], v[220:223], v[236:239], v[62:65]
	ds_read_b128 v[232:235], v245 offset:6144
	ds_read_b128 v[236:239], v246 offset:6144
	s_waitcnt lgkmcnt(2)
	v_mfma_f32_16x16x32_bf16 v[134:137], v[192:195], v[224:227], v[134:137]
	v_mfma_f32_16x16x32_bf16 v[114:117], v[200:203], v[224:227], v[114:117]
	v_mfma_f32_16x16x32_bf16 v[86:89], v[208:211], v[224:227], v[86:89]
	v_mfma_f32_16x16x32_bf16 v[54:57], v[216:219], v[224:227], v[54:57]
	v_mfma_f32_16x16x32_bf16 v[134:137], v[196:199], v[228:231], v[134:137]
	v_mfma_f32_16x16x32_bf16 v[114:117], v[204:207], v[228:231], v[114:117]
	v_mfma_f32_16x16x32_bf16 v[86:89], v[212:215], v[228:231], v[86:89]
	v_mfma_f32_16x16x32_bf16 v[54:57], v[220:223], v[228:231], v[54:57]
	ds_read_b128 v[224:227], v245 offset:8192
	ds_read_b128 v[228:231], v246 offset:8192
	s_waitcnt lgkmcnt(2)
	v_mfma_f32_16x16x32_bf16 v[126:129], v[192:195], v[232:235], v[126:129]
	v_mfma_f32_16x16x32_bf16 v[102:105], v[200:203], v[232:235], v[102:105]
	v_mfma_f32_16x16x32_bf16 v[70:73], v[208:211], v[232:235], v[70:73]
	v_mfma_f32_16x16x32_bf16 v[42:45], v[216:219], v[232:235], v[42:45]
	v_mfma_f32_16x16x32_bf16 v[126:129], v[196:199], v[236:239], v[126:129]
	v_mfma_f32_16x16x32_bf16 v[102:105], v[204:207], v[236:239], v[102:105]
	v_mfma_f32_16x16x32_bf16 v[70:73], v[212:215], v[236:239], v[70:73]
	v_mfma_f32_16x16x32_bf16 v[42:45], v[220:223], v[236:239], v[42:45]
	ds_read_b128 v[232:235], v245 offset:10240
	ds_read_b128 v[236:239], v246 offset:10240
	s_waitcnt lgkmcnt(2)
	v_mfma_f32_16x16x32_bf16 v[118:121], v[192:195], v[224:227], v[118:121]
	v_mfma_f32_16x16x32_bf16 v[90:93], v[200:203], v[224:227], v[90:93]
	v_mfma_f32_16x16x32_bf16 v[58:61], v[208:211], v[224:227], v[58:61]
	v_mfma_f32_16x16x32_bf16 v[34:37], v[216:219], v[224:227], v[34:37]
	v_mfma_f32_16x16x32_bf16 v[118:121], v[196:199], v[228:231], v[118:121]
	v_mfma_f32_16x16x32_bf16 v[90:93], v[204:207], v[228:231], v[90:93]
	v_mfma_f32_16x16x32_bf16 v[58:61], v[212:215], v[228:231], v[58:61]
	v_mfma_f32_16x16x32_bf16 v[34:37], v[220:223], v[228:231], v[34:37]
	ds_read_b128 v[224:227], v245 offset:12288
	ds_read_b128 v[228:231], v246 offset:12288
	s_waitcnt lgkmcnt(2)
	v_mfma_f32_16x16x32_bf16 v[106:109], v[192:195], v[232:235], v[106:109]
	v_mfma_f32_16x16x32_bf16 v[74:77], v[200:203], v[232:235], v[74:77]
	v_mfma_f32_16x16x32_bf16 v[46:49], v[208:211], v[232:235], v[46:49]
	v_mfma_f32_16x16x32_bf16 v[26:29], v[216:219], v[232:235], v[26:29]
	v_mfma_f32_16x16x32_bf16 v[106:109], v[196:199], v[236:239], v[106:109]
	v_mfma_f32_16x16x32_bf16 v[74:77], v[204:207], v[236:239], v[74:77]
	v_mfma_f32_16x16x32_bf16 v[46:49], v[212:215], v[236:239], v[46:49]
	v_mfma_f32_16x16x32_bf16 v[26:29], v[220:223], v[236:239], v[26:29]
	ds_read_b128 v[232:235], v245 offset:14336
	ds_read_b128 v[236:239], v246 offset:14336
	s_waitcnt lgkmcnt(2)
	v_mfma_f32_16x16x32_bf16 v[98:101], v[192:195], v[224:227], v[98:101]
	v_mfma_f32_16x16x32_bf16 v[66:69], v[200:203], v[224:227], v[66:69]
	v_mfma_f32_16x16x32_bf16 v[38:41], v[208:211], v[224:227], v[38:41]
	v_mfma_f32_16x16x32_bf16 v[22:25], v[216:219], v[224:227], v[22:25]
	v_mfma_f32_16x16x32_bf16 v[98:101], v[196:199], v[228:231], v[98:101]
	v_mfma_f32_16x16x32_bf16 v[66:69], v[204:207], v[228:231], v[66:69]
	v_mfma_f32_16x16x32_bf16 v[38:41], v[212:215], v[228:231], v[38:41]
	v_mfma_f32_16x16x32_bf16 v[22:25], v[220:223], v[228:231], v[22:25]
	s_waitcnt lgkmcnt(0)
	v_mfma_f32_16x16x32_bf16 v[82:85], v[192:195], v[232:235], v[82:85]
	v_mfma_f32_16x16x32_bf16 v[50:53], v[200:203], v[232:235], v[50:53]
	v_mfma_f32_16x16x32_bf16 v[30:33], v[208:211], v[232:235], v[30:33]
	v_mfma_f32_16x16x32_bf16 v[18:21], v[216:219], v[232:235], v[18:21]
	v_mfma_f32_16x16x32_bf16 v[82:85], v[196:199], v[236:239], v[82:85]
	v_mfma_f32_16x16x32_bf16 v[50:53], v[204:207], v[236:239], v[50:53]
	v_mfma_f32_16x16x32_bf16 v[30:33], v[212:215], v[236:239], v[30:33]
	v_mfma_f32_16x16x32_bf16 v[18:21], v[220:223], v[236:239], v[18:21]
	s_nop 7
	s_nop 7
	s_waitcnt vmcnt(6)
	v_add_u32_e32 v153, v157, v155
	s_waitcnt lgkmcnt(0)
	v_and_b32_e32 v1, 0xfffffc0, v1
	v_lshl_or_b32 v1, v149, 2, v1
	v_mul_lo_u32 v1, v1, s33
	v_lshl_or_b32 v1, v147, 2, v1
	s_lshl_b32 s31, s30, 1
	s_mov_b64 s[4:5], -1
	s_cmp_lg_u32 s30, 20
	s_waitcnt lgkmcnt(0)
	s_waitcnt lgkmcnt(0)
	s_waitcnt lgkmcnt(0)
	s_waitcnt lgkmcnt(0)
	s_waitcnt lgkmcnt(0)
	v_mov_b64_e32 v[162:163], v[26:27]
	v_mov_b64_e32 v[164:165], v[28:29]
	s_nop 2
	s_waitcnt lgkmcnt(0)
	v_mov_b64_e32 v[204:205], v[22:23]
	v_mov_b64_e32 v[206:207], v[24:25]
	s_nop 2
	s_waitcnt vmcnt(0)
	v_mov_b64_e32 v[200:201], v[66:67]
	v_mov_b64_e32 v[202:203], v[68:69]
	s_waitcnt vmcnt(0)
	s_nop 0
	v_mov_b32_e32 v66, v15
	v_mov_b32_e32 v67, v16
	v_mov_b32_e32 v68, v11
	s_waitcnt lgkmcnt(0)
	v_mov_b32_e32 v69, v12
	v_mov_b32_e32 v15, v17
	v_mov_b32_e32 v11, v13
	v_pk_add_f32 v[14:15], v[66:67], v[14:15]
	v_pk_add_f32 v[10:11], v[68:69], v[10:11]
	v_mov_b64_e32 v[158:159], v[30:31]
	v_mov_b64_e32 v[160:161], v[32:33]
	v_pk_add_f32 v[14:15], v[14:15], v[14:15] op_sel:[0,1] op_sel_hi:[1,0]
	v_pk_add_f32 v[16:17], v[10:11], v[10:11] op_sel:[0,1] op_sel_hi:[1,0]
	v_mov_b32_e32 v15, v2
	v_mov_b64_e32 v[192:193], v[18:19]
	v_mov_b64_e32 v[194:195], v[20:21]
	s_nop 1
	v_mov_b32_e32 v17, v3
	s_waitcnt lgkmcnt(3)
	v_mov_b64_e32 v[22:23], v[142:143]
	v_mov_b64_e32 v[24:25], v[144:145]
	v_add_f32_e64 v14, v14, v16
	v_add_f32_e64 v15, v15, v17
	s_nop 0
	s_waitcnt lgkmcnt(3)
	v_mov_b64_e32 v[30:31], v[130:131]
	v_mov_b64_e32 v[32:33], v[132:133]
	s_waitcnt lgkmcnt(0)
	v_mov_b32_e32 v26, v7
	v_pk_add_f32 v[66:67], v[6:7], v[26:27]
	v_mov_b32_e32 v6, v9
	v_pk_add_f32 v[68:69], v[8:9], v[6:7]
	v_mov_b32_e32 v67, v4
	v_mov_b32_e32 v69, v5
	v_pk_add_f32 v[16:17], v[66:67], v[68:69]
	v_pk_add_f32 v[14:15], v[14:15], v[16:17]
	v_mov_b64_e32 v[26:27], v[122:123]
	v_mov_b64_e32 v[28:29], v[124:125]
	v_add_f32_e32 v14, v14, v15
	v_fmamk_f32 v14, v14, 0x3a800000, v172
	v_mul_f32_e32 v15, 0x4b800000, v14
	v_cmp_gt_f32_e32 vcc, s58, v14
	v_mov_b64_e32 v[122:123], v[94:95]
	v_mov_b64_e32 v[124:125], v[96:97]
	s_nop 2
	v_cndmask_b32_e32 v14, v14, v15, vcc
	v_rsq_f32_e32 v14, v14
	v_mov_b64_e32 v[10:11], v[138:139]
	v_mov_b64_e32 v[12:13], v[140:141]
	v_add_u32_e32 v67, 0x1000, v1
	v_mul_f32_e32 v15, 0x45800000, v14
	v_cndmask_b32_e32 v66, v14, v15, vcc
	s_waitcnt lgkmcnt(3)
	v_mov_b64_e32 v[18:19], v[134:135]
	v_mov_b64_e32 v[20:21], v[136:137]
	s_waitcnt lgkmcnt(2)
	v_mov_b64_e32 v[6:7], v[126:127]
	v_mov_b64_e32 v[8:9], v[128:129]
	s_nop 2
	s_waitcnt lgkmcnt(0)
	s_barrier
	ds_write2_b32 v1, v22, v10 offset1:16
	ds_write2_b32 v1, v23, v11 offset0:68 offset1:84
	ds_write2_b32 v1, v24, v12 offset0:136 offset1:152
	ds_write2_b32 v1, v25, v13 offset0:204 offset1:220
	ds_write2_b32 v1, v18, v6 offset0:32 offset1:48
	ds_write2_b32 v1, v19, v7 offset0:100 offset1:116
	v_mov_b32_e32 v68, v70
	v_mov_b32_e32 v69, v71
	v_mov_b32_e32 v70, v72
	v_mov_b32_e32 v71, v73
	ds_write2_b32 v1, v20, v8 offset0:168 offset1:184
	ds_write2_b32 v1, v21, v9 offset0:236 offset1:252
	ds_write2_b32 v67, v30, v26 offset0:64 offset1:80
	ds_write2_b32 v67, v31, v27 offset0:132 offset1:148
	ds_write2_b32 v67, v32, v28 offset0:200 offset1:216
	v_mov_b64_e32 v[138:139], v[42:43]
	v_mov_b64_e32 v[140:141], v[44:45]
	v_mov_b64_e32 v[14:15], v[118:119]
	v_mov_b64_e32 v[16:17], v[120:121]
	v_mov_b64_e32 v[10:11], v[90:91]
	v_mov_b64_e32 v[12:13], v[92:93]
	v_mov_b64_e32 v[6:7], v[58:59]
	v_mov_b64_e32 v[8:9], v[60:61]
	v_mov_b64_e32 v[2:3], v[34:35]
	v_mov_b64_e32 v[4:5], v[36:37]
	v_add_u32_e32 v94, 0x1400, v1
	v_add_u32_e32 v95, 0x2000, v1
	v_add_u32_e32 v96, 0x2400, v1
	v_mov_b64_e32 v[22:23], v[46:47]
	v_mov_b64_e32 v[24:25], v[48:49]
	v_add_u32_e32 v97, 0x3000, v1
	ds_write2_b32 v94, v33, v29 offset0:12 offset1:28
	ds_write2_b32 v67, v114, v102 offset0:96 offset1:112
	ds_write2_b32 v67, v115, v103 offset0:164 offset1:180
	ds_write2_b32 v67, v116, v104 offset0:232 offset1:248
	ds_write2_b32 v94, v117, v105 offset0:44 offset1:60
	v_mov_b64_e32 v[46:47], v[98:99]
	v_mov_b64_e32 v[48:49], v[100:101]
	ds_write2_b32 v95, v110, v122 offset0:128 offset1:144
	ds_write2_b32 v95, v111, v123 offset0:196 offset1:212
	ds_write2_b32 v96, v112, v124 offset0:8 offset1:24
	ds_write2_b32 v96, v113, v125 offset0:76 offset1:92
	v_add_u32_e32 v98, 0x3400, v1
	v_mov_b64_e32 v[30:31], v[106:107]
	v_mov_b64_e32 v[32:33], v[108:109]
	ds_write2_b32 v95, v86, v68 offset0:160 offset1:176
	ds_write2_b32 v95, v87, v69 offset0:228 offset1:244
	ds_write2_b32 v96, v88, v70 offset0:40 offset1:56
	ds_write2_b32 v96, v89, v71 offset0:108 offset1:124
	ds_write2_b32 v97, v78, v62 offset0:192 offset1:208
	v_mov_b64_e32 v[26:27], v[74:75]
	v_mov_b64_e32 v[28:29], v[76:77]
	ds_write2_b32 v98, v79, v63 offset0:4 offset1:20
	ds_write2_b32 v98, v80, v64 offset0:72 offset1:88
	ds_write2_b32 v98, v81, v65 offset0:140 offset1:156
	ds_write2_b32 v97, v54, v138 offset0:224 offset1:240
	ds_write2_b32 v98, v55, v139 offset0:36 offset1:52
	ds_write2_b32 v98, v56, v140 offset0:104 offset1:120
	ds_write2_b32 v98, v57, v141 offset0:172 offset1:188
	v_mov_b64_e32 v[18:19], v[162:163]
	v_mov_b64_e32 v[20:21], v[164:165]
	v_mov_b32_e32 v100, v170
	s_waitcnt lgkmcnt(0)
	s_barrier
	v_mov_b64_e32 v[42:43], v[200:201]
	v_mov_b64_e32 v[44:45], v[202:203]
	v_add_u32_e32 v68, s71, v100
	v_ashrrev_i32_e32 v69, 31, v68
	v_mul_lo_u32 v99, v100, s33
	v_mov_b64_e32 v[34:35], v[204:205]
	v_mov_b64_e32 v[36:37], v[206:207]
	v_mov_b64_e32 v[62:63], v[82:83]
	v_mov_b64_e32 v[64:65], v[84:85]
	v_mov_b64_e32 v[58:59], v[50:51]
	v_mov_b64_e32 v[60:61], v[52:53]
	v_mov_b64_e32 v[54:55], v[158:159]
	v_mov_b64_e32 v[56:57], v[160:161]
	v_mov_b64_e32 v[50:51], v[192:193]
	v_mov_b64_e32 v[52:53], v[194:195]
	s_cbranch_scc0 .LBB0_570
	v_cmp_gt_i32_e32 vcc, s78, v68
	s_nop 1
	v_cndmask_b32_e32 v70, v179, v173, vcc
	v_and_b32_e32 v101, v70, v68
	v_mov_b64_e32 v[70:71], s[38:39]
	v_mad_i64_i32 v[70:71], s[4:5], v68, s59, v[70:71]
	s_lshl_b32 s4, s30, 7
	s_ashr_i32 s5, s4, 31
	v_lshl_add_u64 v[70:71], s[4:5], 1, v[70:71]
	s_sub_i32 s4, s31, 28
	s_cmp_gt_u32 s4, 9
	s_mov_b64 s[4:5], -1
	s_cbranch_scc0 .LBB0_566
	s_cmp_lt_i32 s30, 2
	v_mul_f32_e32 v72, 0x3e38aa3b, v66
	s_cselect_b64 vcc, -1, 0
	s_cmp_lt_i32 s30, 4
	v_cndmask_b32_e32 v72, v66, v72, vcc
	s_cselect_b64 s[6:7], -1, 0
	v_lshlrev_b32_e32 v74, 6, v101
	v_mov_b32_e32 v75, v0
	v_lshl_add_u64 v[74:75], s[16:17], 0, v[74:75]
	v_mov_b32_e32 v73, v72
	s_mov_b32 s4, 0
	s_xor_b64 s[6:7], s[6:7], -1
	v_mov_b64_e32 v[76:77], v[70:71]
	s_branch .LBB0_562
